# GEMM2b stagger 24us instead of 16us
# baseline (speedup 1.0000x reference)
; #define WSB_DECL unsigned char* wsb = A.ws; asm volatile("" : "+s"(wsb))
; __global__ void __launch_bounds__(NWAVES * 64, 2) hybrid_fwd(Args A) {
;     ...
;     for (int ph = lo; ph < hi; ++ph) {
;       const int l = (ph - 1) / 6, s = (ph == 0) ? -1 : (ph - 1) % 6;
;       WSB_DECL;
;       const int reps = ((ph > 0 && ((DUP_MASK >> s) & 1) && !(s == 5 && l == DEPTH - 1)) || (ph == 0 && (DUP_MASK & 64))) ? 2 : 1;
;       for (int rep = 0; rep < reps; ++rep) {
;         if (rep) { if (ph == 0) cg::this_grid().sync(); else xcd_barrier(bar); }
;         if (ph == 0) { if (EN(0)) phase_prologue(A, C); }
;         else {
;             if (s == 0 && EN(1)) { pg8::Gemm g{WS_PTR(const bf16, WS_HB), WS_PTR(const bf16, WS_WINT) + (size_t)l * DINP * D, M, DINP, D, D}; pg8::StaticOrder S; S.init(M, DINP, C.G, C.bid);
;                 pg8::EpiU E{WS_PTR(bf16, WS_U), WS_PTR(const float, WS_SS) + (size_t)l * M};
;                 pg8::gemm_phase<pg8::EpiU, pg8::StaticOrder, G1_ALIGN, G1_SP2>(C.lds, g, S, E); }
;             else if (s == 1 && EN(2)) phase_prep(A, C, l);
;             else if ((s == 2 && EN(3)) || (s == 3 && EN(4)) || (s == 4 && EN(5))) {
;                 const bool split = C.G >= 192; bool go = (s == 4); int k0 = split ? KSPLIT : 0, kl = D - k0, gg = C.G, cc = C.bid, mrows = M; size_t roff = 0;
;                 if (s == 2) { go = phase_mixers(A, C, l, rep ? DUP_UN : 7); k0 = 0; kl = KSPLIT; gg = C.G - 128; cc = C.bid - 128; mrows = MP; }
.LBB0_19:
	s_mov_b64 s[0:1], s[24:25]
	v_writelane_b32 v255, s0, 36
	s_nop 1
	v_writelane_b32 v255, s1, 37
	v_writelane_b32 v255, s2, 38
	v_writelane_b32 v255, s3, 39
	v_sub_co_u32_e64 v0, s[0:1], s24, 1
	s_nop 0
	v_readfirstlane_b32 s2, v0
	s_mul_hi_i32 s3, s2, 0x2aaaaaab
	s_lshr_b32 s8, s3, 31
	s_add_i32 s8, s3, s8
	s_mul_i32 s3, s8, 6
	s_sub_i32 s10, s2, s3
	s_cmp_eq_u32 s10, 5
	s_cselect_b64 s[2:3], -1, 0
	v_writelane_b32 v255, s2, 40
	s_andn2_b64 vcc, exec, s[0:1]
	s_mov_b64 s[0:1], -1
	v_writelane_b32 v255, s3, 41
	s_cmp_eq_u32 s10, 4
	s_cbranch_scc0 .Lmy_nostag4
	v_readlane_b32 s2, v253, 0
	s_nop 0
	s_bitcmp1_b32 s2, 3
	s_cbranch_scc0 .Lmy_nostag4
	s_memrealtime s[98:99]
	s_waitcnt lgkmcnt(0)
	s_add_u32 s2, s98, 2400

.LBB0_685:
	ds_read_b128 v[164:167], v5 offset:0
	ds_read_b128 v[168:171], v5 offset:256
	ds_read_b128 v[172:175], v5 offset:512
	ds_read_b128 v[176:179], v5 offset:768
	ds_read_b128 v[180:183], v5 offset:1024
	ds_read_b32 v184, v9 offset:0
	ds_read_b128 v[186:189], v5 offset:1536
	ds_read_b128 v[190:193], v5 offset:1792
	ds_read_b128 v[194:197], v5 offset:2048
	ds_read_b128 v[198:201], v5 offset:2304
	ds_read_b128 v[202:205], v5 offset:2560
	ds_read_b32 v206, v9 offset:1536
	s_waitcnt lgkmcnt(0)
	v_mul_f32 v137, v184, v176
	v_mul_f32 v138, v184, v177
	v_mul_f32 v145, v2, v164
	v_fma_f32 v145, v13, v165, v145
	v_fma_f32 v145, v12, v166, v145
	v_fma_f32 v145, v8, v167, v145
	ds_read_b128 v[208:211], v5 offset:3072
	ds_read_b128 v[212:215], v5 offset:3328
	ds_read_b128 v[216:219], v5 offset:3584
	ds_read_b128 v[220:223], v5 offset:3840
	ds_read_b128 v[224:227], v5 offset:4096
	ds_read_b32 v228, v9 offset:3072
	v_add_f32_dpp v145, v145, v145 quad_perm:[1,0,3,2] row_mask:0xf bank_mask:0xf bound_ctrl:1
	s_nop 0
	s_nop 0
	v_add_f32_dpp v145, v145, v145 quad_perm:[2,3,0,1] row_mask:0xf bank_mask:0xf bound_ctrl:1
	s_nop 0
	s_nop 0
	v_add_f32_dpp v145, v145, v145 row_half_mirror row_mask:0xf bank_mask:0xf bound_ctrl:1
	v_mul_f32 v139, v184, v178
	v_mul_f32 v140, v184, v179
	v_add_f32_dpp v145, v145, v145 row_mirror row_mask:0xf bank_mask:0xf bound_ctrl:1
	v_fma_f32 v137, -v145, v168, v137
	v_fma_f32 v138, -v145, v169, v138
	v_fma_f32 v139, -v145, v170, v139
	v_fma_f32 v140, -v145, v171, v140
	v_fma_f32 v2, v2, v172, v137
	v_fma_f32 v13, v13, v173, v138
	v_fma_f32 v12, v12, v174, v139
	v_fma_f32 v8, v8, v175, v140
	s_waitcnt lgkmcnt(6)
	v_mul_f32 v137, v206, v198
	v_mul_f32 v138, v206, v199
	v_mul_f32 v145, v2, v186
	v_fma_f32 v145, v13, v187, v145
	v_fma_f32 v145, v12, v188, v145
	v_fma_f32 v145, v8, v189, v145
	ds_read_b128 v[230:233], v5 offset:4608
	ds_read_b128 v[234:237], v5 offset:4864
	ds_read_b128 v[238:241], v5 offset:5120
	ds_read_b128 v[242:245], v5 offset:5376
	ds_read_b128 v[246:249], v5 offset:5632
	ds_read_b32 v250, v9 offset:4608
	v_add_f32_dpp v145, v145, v145 quad_perm:[1,0,3,2] row_mask:0xf bank_mask:0xf bound_ctrl:1
	v_mul_f32 v148, v2, v180
	v_fma_f32 v148, v13, v181, v148
	v_add_f32_dpp v145, v145, v145 quad_perm:[2,3,0,1] row_mask:0xf bank_mask:0xf bound_ctrl:1
	v_fma_f32 v148, v12, v182, v148
	v_fma_f32 v148, v8, v183, v148
	v_add_f32_dpp v145, v145, v145 row_half_mirror row_mask:0xf bank_mask:0xf bound_ctrl:1
	v_mul_f32 v139, v206, v200
	v_mul_f32 v140, v206, v201
	v_add_f32_dpp v145, v145, v145 row_mirror row_mask:0xf bank_mask:0xf bound_ctrl:1
	v_fma_f32 v137, -v145, v190, v137
	v_fma_f32 v138, -v145, v191, v138
	v_fma_f32 v139, -v145, v192, v139
	v_fma_f32 v140, -v145, v193, v140
	v_fma_f32 v2, v2, v194, v137
	v_fma_f32 v13, v13, v195, v138
	v_fma_f32 v12, v12, v196, v139
	v_fma_f32 v8, v8, v197, v140
	s_waitcnt lgkmcnt(6)
	v_mul_f32 v137, v228, v220
	v_mul_f32 v138, v228, v221
	v_mul_f32 v145, v2, v208
	v_fma_f32 v145, v13, v209, v145
	v_fma_f32 v145, v12, v210, v145
	v_fma_f32 v145, v8, v211, v145
	ds_read_b128 v[164:167], v5 offset:6144
	ds_read_b128 v[168:171], v5 offset:6400
	ds_read_b128 v[172:175], v5 offset:6656
	ds_read_b128 v[176:179], v5 offset:6912
	ds_read_b128 v[180:183], v5 offset:7168
	ds_read_b32 v184, v9 offset:6144
	v_add_f32_dpp v145, v145, v145 quad_perm:[1,0,3,2] row_mask:0xf bank_mask:0xf bound_ctrl:1
	v_mul_f32 v149, v2, v202
	v_fma_f32 v149, v13, v203, v149
	v_add_f32_dpp v145, v145, v145 quad_perm:[2,3,0,1] row_mask:0xf bank_mask:0xf bound_ctrl:1
	v_fma_f32 v149, v12, v204, v149
	v_fma_f32 v149, v8, v205, v149
	v_add_f32_dpp v145, v145, v145 row_half_mirror row_mask:0xf bank_mask:0xf bound_ctrl:1
	v_mul_f32 v139, v228, v222
	v_mul_f32 v140, v228, v223
	v_add_f32_dpp v145, v145, v145 row_mirror row_mask:0xf bank_mask:0xf bound_ctrl:1
	v_fma_f32 v137, -v145, v212, v137
	v_fma_f32 v138, -v145, v213, v138
	v_fma_f32 v139, -v145, v214, v139
	v_fma_f32 v140, -v145, v215, v140
	v_fma_f32 v2, v2, v216, v137
	v_fma_f32 v13, v13, v217, v138
	v_fma_f32 v12, v12, v218, v139
	v_fma_f32 v8, v8, v219, v140
	s_waitcnt lgkmcnt(6)
	v_mul_f32 v137, v250, v242
	v_mul_f32 v138, v250, v243
	v_mul_f32 v145, v2, v230
	v_fma_f32 v145, v13, v231, v145
	v_fma_f32 v145, v12, v232, v145
	v_fma_f32 v145, v8, v233, v145
	ds_read_b128 v[186:189], v5 offset:7680
	ds_read_b128 v[190:193], v5 offset:7936
	ds_read_b128 v[194:197], v5 offset:8192
	ds_read_b128 v[198:201], v5 offset:8448
	ds_read_b128 v[202:205], v5 offset:8704
	ds_read_b32 v206, v9 offset:7680
	v_add_f32_dpp v145, v145, v145 quad_perm:[1,0,3,2] row_mask:0xf bank_mask:0xf bound_ctrl:1
	v_mul_f32 v150, v2, v224
	v_fma_f32 v150, v13, v225, v150
	v_add_f32_dpp v145, v145, v145 quad_perm:[2,3,0,1] row_mask:0xf bank_mask:0xf bound_ctrl:1
	v_fma_f32 v150, v12, v226, v150
	v_fma_f32 v150, v8, v227, v150
	v_add_f32_dpp v145, v145, v145 row_half_mirror row_mask:0xf bank_mask:0xf bound_ctrl:1
	v_mul_f32 v139, v250, v244
	v_mul_f32 v140, v250, v245
	v_add_f32_dpp v145, v145, v145 row_mirror row_mask:0xf bank_mask:0xf bound_ctrl:1
	v_fma_f32 v137, -v145, v234, v137
	v_fma_f32 v138, -v145, v235, v138
	v_fma_f32 v139, -v145, v236, v139
	v_fma_f32 v140, -v145, v237, v140
	v_fma_f32 v2, v2, v238, v137
	v_fma_f32 v13, v13, v239, v138
	v_fma_f32 v12, v12, v240, v139
	v_fma_f32 v8, v8, v241, v140
	s_waitcnt lgkmcnt(6)
	v_mul_f32 v137, v184, v176
	v_mul_f32 v138, v184, v177
	v_mul_f32 v145, v2, v164
	v_fma_f32 v145, v13, v165, v145
	v_fma_f32 v145, v12, v166, v145
	v_fma_f32 v145, v8, v167, v145
	ds_read_b128 v[208:211], v5 offset:9216
	ds_read_b128 v[212:215], v5 offset:9472
	ds_read_b128 v[216:219], v5 offset:9728
	ds_read_b128 v[220:223], v5 offset:9984
	ds_read_b128 v[224:227], v5 offset:10240
	ds_read_b32 v228, v9 offset:9216
	v_add_f32_dpp v145, v145, v145 quad_perm:[1,0,3,2] row_mask:0xf bank_mask:0xf bound_ctrl:1
	v_mul_f32 v151, v2, v246
	v_fma_f32 v151, v13, v247, v151
	v_add_f32_dpp v145, v145, v145 quad_perm:[2,3,0,1] row_mask:0xf bank_mask:0xf bound_ctrl:1
	v_fma_f32 v151, v12, v248, v151
	v_fma_f32 v151, v8, v249, v151
	v_add_f32_dpp v145, v145, v145 row_half_mirror row_mask:0xf bank_mask:0xf bound_ctrl:1
	v_mul_f32 v139, v184, v178
	v_mul_f32 v140, v184, v179
	v_add_f32_dpp v145, v145, v145 row_mirror row_mask:0xf bank_mask:0xf bound_ctrl:1
	v_fma_f32 v137, -v145, v168, v137
	v_fma_f32 v138, -v145, v169, v138
	v_fma_f32 v139, -v145, v170, v139
	v_fma_f32 v140, -v145, v171, v140
	v_fma_f32 v2, v2, v172, v137
	v_fma_f32 v13, v13, v173, v138
	v_fma_f32 v12, v12, v174, v139
	v_fma_f32 v8, v8, v175, v140
	s_waitcnt lgkmcnt(6)
	v_mul_f32 v137, v206, v198
	v_mul_f32 v138, v206, v199
	v_mul_f32 v145, v2, v186
	v_fma_f32 v145, v13, v187, v145
	v_fma_f32 v145, v12, v188, v145
	v_fma_f32 v145, v8, v189, v145
	ds_read_b128 v[230:233], v5 offset:10752
	ds_read_b128 v[234:237], v5 offset:11008
	ds_read_b128 v[238:241], v5 offset:11264
	ds_read_b128 v[242:245], v5 offset:11520
	ds_read_b128 v[246:249], v5 offset:11776
	ds_read_b32 v250, v9 offset:10752
	v_add_f32_dpp v145, v145, v145 quad_perm:[1,0,3,2] row_mask:0xf bank_mask:0xf bound_ctrl:1
	v_mul_f32 v152, v2, v180
	v_fma_f32 v152, v13, v181, v152
	v_add_f32_dpp v145, v145, v145 quad_perm:[2,3,0,1] row_mask:0xf bank_mask:0xf bound_ctrl:1
	v_fma_f32 v152, v12, v182, v152
	v_fma_f32 v152, v8, v183, v152
	v_add_f32_dpp v145, v145, v145 row_half_mirror row_mask:0xf bank_mask:0xf bound_ctrl:1
	v_mul_f32 v139, v206, v200
	v_mul_f32 v140, v206, v201
	v_add_f32_dpp v145, v145, v145 row_mirror row_mask:0xf bank_mask:0xf bound_ctrl:1
	v_fma_f32 v137, -v145, v190, v137
	v_fma_f32 v138, -v145, v191, v138
	v_fma_f32 v139, -v145, v192, v139
	v_fma_f32 v140, -v145, v193, v140
	v_fma_f32 v2, v2, v194, v137
	v_fma_f32 v13, v13, v195, v138
	v_fma_f32 v12, v12, v196, v139
	v_fma_f32 v8, v8, v197, v140
	s_waitcnt lgkmcnt(6)
	v_mul_f32 v137, v228, v220
	v_mul_f32 v138, v228, v221
	v_mul_f32 v145, v2, v208
	v_fma_f32 v145, v13, v209, v145
	v_fma_f32 v145, v12, v210, v145
	v_fma_f32 v145, v8, v211, v145
	ds_read_b128 v[164:167], v5 offset:12288
	ds_read_b128 v[168:171], v5 offset:12544
	ds_read_b128 v[172:175], v5 offset:12800
	ds_read_b128 v[176:179], v5 offset:13056
	ds_read_b128 v[180:183], v5 offset:13312
	ds_read_b32 v184, v9 offset:12288
	v_add_f32_dpp v145, v145, v145 quad_perm:[1,0,3,2] row_mask:0xf bank_mask:0xf bound_ctrl:1
	v_mul_f32 v153, v2, v202
	v_fma_f32 v153, v13, v203, v153
	v_add_f32_dpp v145, v145, v145 quad_perm:[2,3,0,1] row_mask:0xf bank_mask:0xf bound_ctrl:1
	v_fma_f32 v153, v12, v204, v153
	v_fma_f32 v153, v8, v205, v153
	v_add_f32_dpp v145, v145, v145 row_half_mirror row_mask:0xf bank_mask:0xf bound_ctrl:1
	v_mul_f32 v139, v228, v222
	v_mul_f32 v140, v228, v223
	v_add_f32_dpp v145, v145, v145 row_mirror row_mask:0xf bank_mask:0xf bound_ctrl:1
	v_fma_f32 v137, -v145, v212, v137
	v_fma_f32 v138, -v145, v213, v138
	v_fma_f32 v139, -v145, v214, v139
	v_fma_f32 v140, -v145, v215, v140
	v_fma_f32 v2, v2, v216, v137
	v_fma_f32 v13, v13, v217, v138
	v_fma_f32 v12, v12, v218, v139
	v_fma_f32 v8, v8, v219, v140
	s_waitcnt lgkmcnt(6)
	v_mul_f32 v137, v250, v242
	v_mul_f32 v138, v250, v243
	v_mul_f32 v145, v2, v230
	v_fma_f32 v145, v13, v231, v145
	v_fma_f32 v145, v12, v232, v145
	v_fma_f32 v145, v8, v233, v145
	ds_read_b128 v[186:189], v5 offset:13824
	ds_read_b128 v[190:193], v5 offset:14080
	ds_read_b128 v[194:197], v5 offset:14336
	ds_read_b128 v[198:201], v5 offset:14592
	ds_read_b128 v[202:205], v5 offset:14848
	ds_read_b32 v206, v9 offset:13824
	v_add_f32_dpp v145, v145, v145 quad_perm:[1,0,3,2] row_mask:0xf bank_mask:0xf bound_ctrl:1
	v_mul_f32 v154, v2, v224
	v_fma_f32 v154, v13, v225, v154
	v_add_f32_dpp v145, v145, v145 quad_perm:[2,3,0,1] row_mask:0xf bank_mask:0xf bound_ctrl:1
	v_fma_f32 v154, v12, v226, v154
	v_fma_f32 v154, v8, v227, v154
	v_add_f32_dpp v145, v145, v145 row_half_mirror row_mask:0xf bank_mask:0xf bound_ctrl:1
	v_mul_f32 v139, v250, v244
	v_mul_f32 v140, v250, v245
	v_add_f32_dpp v145, v145, v145 row_mirror row_mask:0xf bank_mask:0xf bound_ctrl:1
	v_fma_f32 v137, -v145, v234, v137
	v_fma_f32 v138, -v145, v235, v138
	v_fma_f32 v139, -v145, v236, v139
	v_fma_f32 v140, -v145, v237, v140
	v_fma_f32 v2, v2, v238, v137
	v_fma_f32 v13, v13, v239, v138
	v_fma_f32 v12, v12, v240, v139
	v_fma_f32 v8, v8, v241, v140
	s_waitcnt lgkmcnt(6)
	v_mul_f32 v137, v184, v176
	v_mul_f32 v138, v184, v177
	v_mul_f32 v145, v2, v164
	v_fma_f32 v145, v13, v165, v145
	v_fma_f32 v145, v12, v166, v145
	v_fma_f32 v145, v8, v167, v145
	ds_read_b128 v[208:211], v5 offset:15360
	ds_read_b128 v[212:215], v5 offset:15616
	ds_read_b128 v[216:219], v5 offset:15872
	ds_read_b128 v[220:223], v5 offset:16128
	ds_read_b128 v[224:227], v5 offset:16384
	ds_read_b32 v228, v9 offset:15360
	v_add_f32_dpp v145, v145, v145 quad_perm:[1,0,3,2] row_mask:0xf bank_mask:0xf bound_ctrl:1
	v_mul_f32 v155, v2, v246
	v_fma_f32 v155, v13, v247, v155
	v_add_f32_dpp v145, v145, v145 quad_perm:[2,3,0,1] row_mask:0xf bank_mask:0xf bound_ctrl:1
	v_fma_f32 v155, v12, v248, v155
	v_fma_f32 v155, v8, v249, v155
	v_add_f32_dpp v145, v145, v145 row_half_mirror row_mask:0xf bank_mask:0xf bound_ctrl:1
	v_mul_f32 v139, v184, v178
	v_mul_f32 v140, v184, v179
	v_add_f32_dpp v145, v145, v145 row_mirror row_mask:0xf bank_mask:0xf bound_ctrl:1
	v_fma_f32 v137, -v145, v168, v137
	v_fma_f32 v138, -v145, v169, v138
	v_fma_f32 v139, -v145, v170, v139
	v_fma_f32 v140, -v145, v171, v140
	v_fma_f32 v2, v2, v172, v137
	v_fma_f32 v13, v13, v173, v138
	v_fma_f32 v12, v12, v174, v139
	v_fma_f32 v8, v8, v175, v140
	s_waitcnt lgkmcnt(6)
	v_mul_f32 v137, v206, v198
	v_mul_f32 v138, v206, v199
	v_mul_f32 v145, v2, v186
	v_fma_f32 v145, v13, v187, v145
	v_fma_f32 v145, v12, v188, v145
	v_fma_f32 v145, v8, v189, v145
	ds_read_b128 v[230:233], v5 offset:16896
	ds_read_b128 v[234:237], v5 offset:17152
	ds_read_b128 v[238:241], v5 offset:17408
	ds_read_b128 v[242:245], v5 offset:17664
	ds_read_b128 v[246:249], v5 offset:17920
	ds_read_b32 v250, v9 offset:16896
	v_add_f32_dpp v145, v145, v145 quad_perm:[1,0,3,2] row_mask:0xf bank_mask:0xf bound_ctrl:1
	v_mul_f32 v156, v2, v180
	v_fma_f32 v156, v13, v181, v156
	v_add_f32_dpp v145, v145, v145 quad_perm:[2,3,0,1] row_mask:0xf bank_mask:0xf bound_ctrl:1
	v_fma_f32 v156, v12, v182, v156
	v_fma_f32 v156, v8, v183, v156
	v_add_f32_dpp v145, v145, v145 row_half_mirror row_mask:0xf bank_mask:0xf bound_ctrl:1
	v_mul_f32 v139, v206, v200
	v_mul_f32 v140, v206, v201
	v_add_f32_dpp v145, v145, v145 row_mirror row_mask:0xf bank_mask:0xf bound_ctrl:1
	v_fma_f32 v137, -v145, v190, v137
	v_fma_f32 v138, -v145, v191, v138
	v_fma_f32 v139, -v145, v192, v139
	v_fma_f32 v140, -v145, v193, v140
	v_fma_f32 v2, v2, v194, v137
	v_fma_f32 v13, v13, v195, v138
	v_fma_f32 v12, v12, v196, v139
	v_fma_f32 v8, v8, v197, v140
	s_waitcnt lgkmcnt(6)
	v_mul_f32 v137, v228, v220
	v_mul_f32 v138, v228, v221
	v_mul_f32 v145, v2, v208
	v_fma_f32 v145, v13, v209, v145
	v_fma_f32 v145, v12, v210, v145
	v_fma_f32 v145, v8, v211, v145
	ds_read_b128 v[164:167], v5 offset:18432
	ds_read_b128 v[168:171], v5 offset:18688
	ds_read_b128 v[172:175], v5 offset:18944
	ds_read_b128 v[176:179], v5 offset:19200
	ds_read_b128 v[180:183], v5 offset:19456
	ds_read_b32 v184, v9 offset:18432
	v_add_f32_dpp v145, v145, v145 quad_perm:[1,0,3,2] row_mask:0xf bank_mask:0xf bound_ctrl:1
	v_mul_f32 v157, v2, v202
	v_fma_f32 v157, v13, v203, v157
	v_add_f32_dpp v145, v145, v145 quad_perm:[2,3,0,1] row_mask:0xf bank_mask:0xf bound_ctrl:1
	v_fma_f32 v157, v12, v204, v157
	v_fma_f32 v157, v8, v205, v157
	v_add_f32_dpp v145, v145, v145 row_half_mirror row_mask:0xf bank_mask:0xf bound_ctrl:1
	v_mul_f32 v139, v228, v222
	v_mul_f32 v140, v228, v223
	v_add_f32_dpp v145, v145, v145 row_mirror row_mask:0xf bank_mask:0xf bound_ctrl:1
	v_fma_f32 v137, -v145, v212, v137
	v_fma_f32 v138, -v145, v213, v138
	v_fma_f32 v139, -v145, v214, v139
	v_fma_f32 v140, -v145, v215, v140
	v_fma_f32 v2, v2, v216, v137
	v_fma_f32 v13, v13, v217, v138
	v_fma_f32 v12, v12, v218, v139
	v_fma_f32 v8, v8, v219, v140
	s_waitcnt lgkmcnt(6)
	v_mul_f32 v137, v250, v242
	v_mul_f32 v138, v250, v243
	v_mul_f32 v145, v2, v230
	v_fma_f32 v145, v13, v231, v145
	v_fma_f32 v145, v12, v232, v145
	v_fma_f32 v145, v8, v233, v145
	ds_read_b128 v[186:189], v5 offset:19968
	ds_read_b128 v[190:193], v5 offset:20224
	ds_read_b128 v[194:197], v5 offset:20480
	ds_read_b128 v[198:201], v5 offset:20736
	ds_read_b128 v[202:205], v5 offset:20992
	ds_read_b32 v206, v9 offset:19968
	v_add_f32_dpp v145, v145, v145 quad_perm:[1,0,3,2] row_mask:0xf bank_mask:0xf bound_ctrl:1
	v_mul_f32 v158, v2, v224
	v_fma_f32 v158, v13, v225, v158
	v_add_f32_dpp v145, v145, v145 quad_perm:[2,3,0,1] row_mask:0xf bank_mask:0xf bound_ctrl:1
	v_fma_f32 v158, v12, v226, v158
	v_fma_f32 v158, v8, v227, v158
	v_add_f32_dpp v145, v145, v145 row_half_mirror row_mask:0xf bank_mask:0xf bound_ctrl:1
	v_mul_f32 v139, v250, v244
	v_mul_f32 v140, v250, v245
	v_add_f32_dpp v145, v145, v145 row_mirror row_mask:0xf bank_mask:0xf bound_ctrl:1
	v_fma_f32 v137, -v145, v234, v137
	v_fma_f32 v138, -v145, v235, v138
	v_fma_f32 v139, -v145, v236, v139
	v_fma_f32 v140, -v145, v237, v140
	v_fma_f32 v2, v2, v238, v137
	v_fma_f32 v13, v13, v239, v138
	v_fma_f32 v12, v12, v240, v139
	v_fma_f32 v8, v8, v241, v140
	s_waitcnt lgkmcnt(6)
	v_mul_f32 v137, v184, v176
	v_mul_f32 v138, v184, v177
	v_mul_f32 v145, v2, v164
	v_fma_f32 v145, v13, v165, v145
	v_fma_f32 v145, v12, v166, v145
	v_fma_f32 v145, v8, v167, v145
	ds_read_b128 v[208:211], v5 offset:21504
	ds_read_b128 v[212:215], v5 offset:21760
	ds_read_b128 v[216:219], v5 offset:22016
	ds_read_b128 v[220:223], v5 offset:22272
	ds_read_b128 v[224:227], v5 offset:22528
	ds_read_b32 v228, v9 offset:21504
	v_add_f32_dpp v145, v145, v145 quad_perm:[1,0,3,2] row_mask:0xf bank_mask:0xf bound_ctrl:1
	v_mul_f32 v159, v2, v246
	v_fma_f32 v159, v13, v247, v159
	v_add_f32_dpp v145, v145, v145 quad_perm:[2,3,0,1] row_mask:0xf bank_mask:0xf bound_ctrl:1
	v_fma_f32 v159, v12, v248, v159
	v_fma_f32 v159, v8, v249, v159
	v_add_f32_dpp v145, v145, v145 row_half_mirror row_mask:0xf bank_mask:0xf bound_ctrl:1
	v_mul_f32 v139, v184, v178
	v_mul_f32 v140, v184, v179
	v_add_f32_dpp v145, v145, v145 row_mirror row_mask:0xf bank_mask:0xf bound_ctrl:1
	v_fma_f32 v137, -v145, v168, v137
	v_fma_f32 v138, -v145, v169, v138
	v_fma_f32 v139, -v145, v170, v139
	v_fma_f32 v140, -v145, v171, v140
	v_fma_f32 v2, v2, v172, v137
	v_fma_f32 v13, v13, v173, v138
	v_fma_f32 v12, v12, v174, v139
	v_fma_f32 v8, v8, v175, v140
	s_waitcnt lgkmcnt(6)
	v_mul_f32 v137, v206, v198
	v_mul_f32 v138, v206, v199
	v_mul_f32 v145, v2, v186
	v_fma_f32 v145, v13, v187, v145
	v_fma_f32 v145, v12, v188, v145
	v_fma_f32 v145, v8, v189, v145
	ds_read_b128 v[230:233], v5 offset:23040
	ds_read_b128 v[234:237], v5 offset:23296
	ds_read_b128 v[238:241], v5 offset:23552
	ds_read_b128 v[242:245], v5 offset:23808
	ds_read_b128 v[246:249], v5 offset:24064
	ds_read_b32 v250, v9 offset:23040
	v_add_f32_dpp v145, v145, v145 quad_perm:[1,0,3,2] row_mask:0xf bank_mask:0xf bound_ctrl:1
	v_mul_f32 v160, v2, v180
	v_fma_f32 v160, v13, v181, v160
	v_add_f32_dpp v145, v145, v145 quad_perm:[2,3,0,1] row_mask:0xf bank_mask:0xf bound_ctrl:1
	v_fma_f32 v160, v12, v182, v160
	v_fma_f32 v160, v8, v183, v160
	v_add_f32_dpp v145, v145, v145 row_half_mirror row_mask:0xf bank_mask:0xf bound_ctrl:1
	v_mul_f32 v139, v206, v200
	v_mul_f32 v140, v206, v201
	v_add_f32_dpp v145, v145, v145 row_mirror row_mask:0xf bank_mask:0xf bound_ctrl:1
	v_fma_f32 v137, -v145, v190, v137
	v_fma_f32 v138, -v145, v191, v138
	v_fma_f32 v139, -v145, v192, v139
	v_fma_f32 v140, -v145, v193, v140
	v_fma_f32 v2, v2, v194, v137
	v_fma_f32 v13, v13, v195, v138
	v_fma_f32 v12, v12, v196, v139
	v_fma_f32 v8, v8, v197, v140
	s_waitcnt lgkmcnt(6)
	v_mul_f32 v137, v228, v220
	v_mul_f32 v138, v228, v221
	v_mul_f32 v145, v2, v208
	v_fma_f32 v145, v13, v209, v145
	v_fma_f32 v145, v12, v210, v145
	v_fma_f32 v145, v8, v211, v145
	ds_read_b128 v[164:167], v5 offset:24576
	ds_read_b128 v[168:171], v5 offset:24832
	ds_read_b128 v[172:175], v5 offset:25088
	ds_read_b128 v[176:179], v5 offset:25344
	ds_read_b128 v[180:183], v5 offset:25600
	ds_read_b32 v184, v9 offset:24576
	v_add_f32_dpp v145, v145, v145 quad_perm:[1,0,3,2] row_mask:0xf bank_mask:0xf bound_ctrl:1
	v_mul_f32 v161, v2, v202
	v_fma_f32 v161, v13, v203, v161
	v_add_f32_dpp v145, v145, v145 quad_perm:[2,3,0,1] row_mask:0xf bank_mask:0xf bound_ctrl:1
	v_fma_f32 v161, v12, v204, v161
	v_fma_f32 v161, v8, v205, v161
	v_add_f32_dpp v145, v145, v145 row_half_mirror row_mask:0xf bank_mask:0xf bound_ctrl:1
	v_mul_f32 v139, v228, v222
	v_mul_f32 v140, v228, v223
	v_add_f32_dpp v145, v145, v145 row_mirror row_mask:0xf bank_mask:0xf bound_ctrl:1
	v_fma_f32 v137, -v145, v212, v137
	v_fma_f32 v138, -v145, v213, v138
	v_fma_f32 v139, -v145, v214, v139
	v_fma_f32 v140, -v145, v215, v140
	v_fma_f32 v2, v2, v216, v137
	v_fma_f32 v13, v13, v217, v138
	v_fma_f32 v12, v12, v218, v139
	v_fma_f32 v8, v8, v219, v140
	s_waitcnt lgkmcnt(6)
	v_mul_f32 v137, v250, v242
	v_mul_f32 v138, v250, v243
	v_mul_f32 v145, v2, v230
	v_fma_f32 v145, v13, v231, v145
	v_fma_f32 v145, v12, v232, v145
	v_fma_f32 v145, v8, v233, v145
	ds_read_b128 v[186:189], v5 offset:26112
	ds_read_b128 v[190:193], v5 offset:26368
	ds_read_b128 v[194:197], v5 offset:26624
	ds_read_b128 v[198:201], v5 offset:26880
	ds_read_b128 v[202:205], v5 offset:27136
	ds_read_b32 v206, v9 offset:26112
	v_add_f32_dpp v145, v145, v145 quad_perm:[1,0,3,2] row_mask:0xf bank_mask:0xf bound_ctrl:1
	v_mul_f32 v162, v2, v224
	v_fma_f32 v162, v13, v225, v162
	v_add_f32_dpp v145, v145, v145 quad_perm:[2,3,0,1] row_mask:0xf bank_mask:0xf bound_ctrl:1
	v_fma_f32 v162, v12, v226, v162
	v_fma_f32 v162, v8, v227, v162
	v_add_f32_dpp v145, v145, v145 row_half_mirror row_mask:0xf bank_mask:0xf bound_ctrl:1
	v_mul_f32 v139, v250, v244
	v_mul_f32 v140, v250, v245
	v_add_f32_dpp v145, v145, v145 row_mirror row_mask:0xf bank_mask:0xf bound_ctrl:1
	v_fma_f32 v137, -v145, v234, v137
	v_fma_f32 v138, -v145, v235, v138
	v_fma_f32 v139, -v145, v236, v139
	v_fma_f32 v140, -v145, v237, v140
	v_fma_f32 v2, v2, v238, v137
	v_fma_f32 v13, v13, v239, v138
	v_fma_f32 v12, v12, v240, v139
	v_fma_f32 v8, v8, v241, v140
	s_waitcnt lgkmcnt(6)
	v_mul_f32 v137, v184, v176
	v_mul_f32 v138, v184, v177
	v_mul_f32 v145, v2, v164
	v_fma_f32 v145, v13, v165, v145
	v_fma_f32 v145, v12, v166, v145
	v_fma_f32 v145, v8, v167, v145
	ds_read_b128 v[208:211], v5 offset:27648
	ds_read_b128 v[212:215], v5 offset:27904
	ds_read_b128 v[216:219], v5 offset:28160
	ds_read_b128 v[220:223], v5 offset:28416
	ds_read_b128 v[224:227], v5 offset:28672
	ds_read_b32 v228, v9 offset:27648
	v_add_f32_dpp v145, v145, v145 quad_perm:[1,0,3,2] row_mask:0xf bank_mask:0xf bound_ctrl:1
	v_mul_f32 v163, v2, v246
	v_fma_f32 v163, v13, v247, v163
	v_add_f32_dpp v145, v145, v145 quad_perm:[2,3,0,1] row_mask:0xf bank_mask:0xf bound_ctrl:1
	v_fma_f32 v163, v12, v248, v163
	v_fma_f32 v163, v8, v249, v163
	v_add_f32_dpp v145, v145, v145 row_half_mirror row_mask:0xf bank_mask:0xf bound_ctrl:1
	v_mul_f32 v139, v184, v178
	v_mul_f32 v140, v184, v179
	v_add_f32_dpp v145, v145, v145 row_mirror row_mask:0xf bank_mask:0xf bound_ctrl:1
	v_fma_f32 v137, -v145, v168, v137
	v_fma_f32 v138, -v145, v169, v138
	v_fma_f32 v139, -v145, v170, v139
	v_fma_f32 v140, -v145, v171, v140
	v_fma_f32 v2, v2, v172, v137
	v_fma_f32 v13, v13, v173, v138
	v_fma_f32 v12, v12, v174, v139
	v_fma_f32 v8, v8, v175, v140
	s_waitcnt lgkmcnt(6)
	v_and_b32 v244, 8, v3
	v_cmp_ne_u32 vcc, 0, v244
	v_cndmask_b32 v244, v156, v148, vcc
	v_cndmask_b32 v245, v157, v149, vcc
	v_cndmask_b32 v246, v158, v150, vcc
	v_cndmask_b32 v247, v159, v151, vcc
	v_cndmask_b32 v230, v148, v156, vcc
	v_cndmask_b32 v231, v149, v157, vcc
	v_cndmask_b32 v232, v150, v158, vcc
	v_cndmask_b32 v233, v151, v159, vcc
	v_add_f32_dpp v230, v244, v230 row_mirror row_mask:0xf bank_mask:0xf bound_ctrl:1
	v_add_f32_dpp v231, v245, v231 row_mirror row_mask:0xf bank_mask:0xf bound_ctrl:1
	v_add_f32_dpp v232, v246, v232 row_mirror row_mask:0xf bank_mask:0xf bound_ctrl:1
	v_add_f32_dpp v233, v247, v233 row_mirror row_mask:0xf bank_mask:0xf bound_ctrl:1
	v_cndmask_b32 v244, v160, v152, vcc
	v_cndmask_b32 v245, v161, v153, vcc
	v_cndmask_b32 v246, v162, v154, vcc
	v_cndmask_b32 v247, v163, v155, vcc
	v_cndmask_b32 v234, v152, v160, vcc
	v_cndmask_b32 v235, v153, v161, vcc
	v_cndmask_b32 v236, v154, v162, vcc
	v_cndmask_b32 v237, v155, v163, vcc
	v_add_f32_dpp v234, v244, v234 row_mirror row_mask:0xf bank_mask:0xf bound_ctrl:1
	v_add_f32_dpp v235, v245, v235 row_mirror row_mask:0xf bank_mask:0xf bound_ctrl:1
	v_add_f32_dpp v236, v246, v236 row_mirror row_mask:0xf bank_mask:0xf bound_ctrl:1
	v_add_f32_dpp v237, v247, v237 row_mirror row_mask:0xf bank_mask:0xf bound_ctrl:1
	v_and_b32 v244, 4, v3
	v_cmp_ne_u32 vcc, 0, v244
	v_cndmask_b32 v244, v234, v230, vcc
	v_cndmask_b32 v245, v235, v231, vcc
	v_cndmask_b32 v246, v236, v232, vcc
	v_cndmask_b32 v247, v237, v233, vcc
	v_cndmask_b32 v238, v230, v234, vcc
	v_cndmask_b32 v239, v231, v235, vcc
	v_cndmask_b32 v240, v232, v236, vcc
	v_cndmask_b32 v241, v233, v237, vcc
	v_add_f32_dpp v238, v244, v238 row_half_mirror row_mask:0xf bank_mask:0xf bound_ctrl:1
	v_add_f32_dpp v239, v245, v239 row_half_mirror row_mask:0xf bank_mask:0xf bound_ctrl:1
	v_add_f32_dpp v240, v246, v240 row_half_mirror row_mask:0xf bank_mask:0xf bound_ctrl:1
	v_add_f32_dpp v241, v247, v241 row_half_mirror row_mask:0xf bank_mask:0xf bound_ctrl:1
	v_and_b32 v244, 2, v3
	v_cmp_ne_u32 vcc, 0, v244
	v_cndmask_b32 v244, v240, v238, vcc
	v_cndmask_b32 v245, v241, v239, vcc
	v_cndmask_b32 v242, v238, v240, vcc
	v_cndmask_b32 v243, v239, v241, vcc
	v_add_f32_dpp v242, v244, v242 quad_perm:[2,3,0,1] row_mask:0xf bank_mask:0xf bound_ctrl:1
	v_add_f32_dpp v243, v245, v243 quad_perm:[2,3,0,1] row_mask:0xf bank_mask:0xf bound_ctrl:1
	v_and_b32 v244, 1, v3
	v_cmp_ne_u32 vcc, 0, v244
	v_cndmask_b32 v244, v243, v242, vcc
	v_cndmask_b32 v245, v242, v243, vcc
	s_nop 0
	v_add_f32_dpp v18, v244, v245 quad_perm:[1,0,3,2] row_mask:0xf bank_mask:0xf bound_ctrl:1
	v_mul_f32 v137, v206, v198
	v_mul_f32 v138, v206, v199
	v_mul_f32 v145, v2, v186
	v_fma_f32 v145, v13, v187, v145
	v_fma_f32 v145, v12, v188, v145
	v_fma_f32 v145, v8, v189, v145
	ds_read_b128 v[230:233], v5 offset:29184
	ds_read_b128 v[234:237], v5 offset:29440
	ds_read_b128 v[238:241], v5 offset:29696
	ds_read_b128 v[242:245], v5 offset:29952
	ds_read_b128 v[246:249], v5 offset:30208
	ds_read_b32 v250, v9 offset:29184
	v_add_f32_dpp v145, v145, v145 quad_perm:[1,0,3,2] row_mask:0xf bank_mask:0xf bound_ctrl:1
	v_mul_f32 v148, v2, v180
	v_fma_f32 v148, v13, v181, v148
	v_add_f32_dpp v145, v145, v145 quad_perm:[2,3,0,1] row_mask:0xf bank_mask:0xf bound_ctrl:1
	v_fma_f32 v148, v12, v182, v148
	v_fma_f32 v148, v8, v183, v148
	v_add_f32_dpp v145, v145, v145 row_half_mirror row_mask:0xf bank_mask:0xf bound_ctrl:1
	v_mul_f32 v139, v206, v200
	v_mul_f32 v140, v206, v201
	v_add_f32_dpp v145, v145, v145 row_mirror row_mask:0xf bank_mask:0xf bound_ctrl:1
	v_fma_f32 v137, -v145, v190, v137
	v_fma_f32 v138, -v145, v191, v138
	v_fma_f32 v139, -v145, v192, v139
	v_fma_f32 v140, -v145, v193, v140
	v_fma_f32 v2, v2, v194, v137
	v_fma_f32 v13, v13, v195, v138
	v_fma_f32 v12, v12, v196, v139
	v_fma_f32 v8, v8, v197, v140
	s_waitcnt lgkmcnt(6)
	v_mul_f32 v137, v228, v220
	v_mul_f32 v138, v228, v221
	v_mul_f32 v145, v2, v208
	v_fma_f32 v145, v13, v209, v145
	v_fma_f32 v145, v12, v210, v145
	v_fma_f32 v145, v8, v211, v145
	ds_read_b128 v[164:167], v5 offset:30720
	ds_read_b128 v[168:171], v5 offset:30976
	ds_read_b128 v[172:175], v5 offset:31232
	ds_read_b128 v[176:179], v5 offset:31488
	ds_read_b128 v[180:183], v5 offset:31744
	ds_read_b32 v184, v9 offset:30720
	v_add_f32_dpp v145, v145, v145 quad_perm:[1,0,3,2] row_mask:0xf bank_mask:0xf bound_ctrl:1
	v_mul_f32 v149, v2, v202
	v_fma_f32 v149, v13, v203, v149
	v_add_f32_dpp v145, v145, v145 quad_perm:[2,3,0,1] row_mask:0xf bank_mask:0xf bound_ctrl:1
	v_fma_f32 v149, v12, v204, v149
	v_fma_f32 v149, v8, v205, v149
	v_add_f32_dpp v145, v145, v145 row_half_mirror row_mask:0xf bank_mask:0xf bound_ctrl:1
	v_mul_f32 v139, v228, v222
	v_mul_f32 v140, v228, v223
	v_add_f32_dpp v145, v145, v145 row_mirror row_mask:0xf bank_mask:0xf bound_ctrl:1
	v_fma_f32 v137, -v145, v212, v137
	v_fma_f32 v138, -v145, v213, v138
	v_fma_f32 v139, -v145, v214, v139
	v_fma_f32 v140, -v145, v215, v140
	v_fma_f32 v2, v2, v216, v137
	v_fma_f32 v13, v13, v217, v138
	v_fma_f32 v12, v12, v218, v139
	v_fma_f32 v8, v8, v219, v140
	s_waitcnt lgkmcnt(6)
	v_mul_f32 v137, v250, v242
	v_mul_f32 v138, v250, v243
	v_mul_f32 v145, v2, v230
	v_fma_f32 v145, v13, v231, v145
	v_fma_f32 v145, v12, v232, v145
	v_fma_f32 v145, v8, v233, v145
	ds_read_b128 v[186:189], v5 offset:32256
	ds_read_b128 v[190:193], v5 offset:32512
	ds_read_b128 v[194:197], v5 offset:32768
	ds_read_b128 v[198:201], v5 offset:33024
	ds_read_b128 v[202:205], v5 offset:33280
	ds_read_b32 v206, v9 offset:32256
	v_add_f32_dpp v145, v145, v145 quad_perm:[1,0,3,2] row_mask:0xf bank_mask:0xf bound_ctrl:1
	v_mul_f32 v150, v2, v224
	v_fma_f32 v150, v13, v225, v150
	v_add_f32_dpp v145, v145, v145 quad_perm:[2,3,0,1] row_mask:0xf bank_mask:0xf bound_ctrl:1
	v_fma_f32 v150, v12, v226, v150
	v_fma_f32 v150, v8, v227, v150
	v_add_f32_dpp v145, v145, v145 row_half_mirror row_mask:0xf bank_mask:0xf bound_ctrl:1
	v_mul_f32 v139, v250, v244
	v_mul_f32 v140, v250, v245
	v_add_f32_dpp v145, v145, v145 row_mirror row_mask:0xf bank_mask:0xf bound_ctrl:1
	v_fma_f32 v137, -v145, v234, v137
	v_fma_f32 v138, -v145, v235, v138
	v_fma_f32 v139, -v145, v236, v139
	v_fma_f32 v140, -v145, v237, v140
	v_fma_f32 v2, v2, v238, v137
	v_fma_f32 v13, v13, v239, v138
	v_fma_f32 v12, v12, v240, v139
	v_fma_f32 v8, v8, v241, v140
	s_waitcnt lgkmcnt(6)
	v_mul_f32 v137, v184, v176
	v_mul_f32 v138, v184, v177
	v_mul_f32 v145, v2, v164
	v_fma_f32 v145, v13, v165, v145
	v_fma_f32 v145, v12, v166, v145
	v_fma_f32 v145, v8, v167, v145
	ds_read_b128 v[208:211], v5 offset:33792
	ds_read_b128 v[212:215], v5 offset:34048
	ds_read_b128 v[216:219], v5 offset:34304
	ds_read_b128 v[220:223], v5 offset:34560
	ds_read_b128 v[224:227], v5 offset:34816
	ds_read_b32 v228, v9 offset:33792
	v_add_f32_dpp v145, v145, v145 quad_perm:[1,0,3,2] row_mask:0xf bank_mask:0xf bound_ctrl:1
	v_mul_f32 v151, v2, v246
	v_fma_f32 v151, v13, v247, v151
	v_add_f32_dpp v145, v145, v145 quad_perm:[2,3,0,1] row_mask:0xf bank_mask:0xf bound_ctrl:1
	v_fma_f32 v151, v12, v248, v151
	v_fma_f32 v151, v8, v249, v151
	v_add_f32_dpp v145, v145, v145 row_half_mirror row_mask:0xf bank_mask:0xf bound_ctrl:1
	v_mul_f32 v139, v184, v178
	v_mul_f32 v140, v184, v179
	v_add_f32_dpp v145, v145, v145 row_mirror row_mask:0xf bank_mask:0xf bound_ctrl:1
	v_fma_f32 v137, -v145, v168, v137
	v_fma_f32 v138, -v145, v169, v138
	v_fma_f32 v139, -v145, v170, v139
	v_fma_f32 v140, -v145, v171, v140
	v_fma_f32 v2, v2, v172, v137
	v_fma_f32 v13, v13, v173, v138
	v_fma_f32 v12, v12, v174, v139
	v_fma_f32 v8, v8, v175, v140
	s_waitcnt lgkmcnt(6)
	v_mul_f32 v137, v206, v198
	v_mul_f32 v138, v206, v199
	v_mul_f32 v145, v2, v186
	v_fma_f32 v145, v13, v187, v145
	v_fma_f32 v145, v12, v188, v145
	v_fma_f32 v145, v8, v189, v145
	ds_read_b128 v[230:233], v5 offset:35328
	ds_read_b128 v[234:237], v5 offset:35584
	ds_read_b128 v[238:241], v5 offset:35840
	ds_read_b128 v[242:245], v5 offset:36096
	ds_read_b128 v[246:249], v5 offset:36352
	ds_read_b32 v250, v9 offset:35328
	v_add_f32_dpp v145, v145, v145 quad_perm:[1,0,3,2] row_mask:0xf bank_mask:0xf bound_ctrl:1
	v_mul_f32 v152, v2, v180
	v_fma_f32 v152, v13, v181, v152
	v_add_f32_dpp v145, v145, v145 quad_perm:[2,3,0,1] row_mask:0xf bank_mask:0xf bound_ctrl:1
	v_fma_f32 v152, v12, v182, v152
	v_fma_f32 v152, v8, v183, v152
	v_add_f32_dpp v145, v145, v145 row_half_mirror row_mask:0xf bank_mask:0xf bound_ctrl:1
	v_mul_f32 v139, v206, v200
	v_mul_f32 v140, v206, v201
	v_add_f32_dpp v145, v145, v145 row_mirror row_mask:0xf bank_mask:0xf bound_ctrl:1
	v_fma_f32 v137, -v145, v190, v137
	v_fma_f32 v138, -v145, v191, v138
	v_fma_f32 v139, -v145, v192, v139
	v_fma_f32 v140, -v145, v193, v140
	v_fma_f32 v2, v2, v194, v137
	v_fma_f32 v13, v13, v195, v138
	v_fma_f32 v12, v12, v196, v139
	v_fma_f32 v8, v8, v197, v140
	s_waitcnt lgkmcnt(6)
	v_mul_f32 v137, v228, v220
	v_mul_f32 v138, v228, v221
	v_mul_f32 v145, v2, v208
	v_fma_f32 v145, v13, v209, v145
	v_fma_f32 v145, v12, v210, v145
	v_fma_f32 v145, v8, v211, v145
	ds_read_b128 v[164:167], v5 offset:36864
	ds_read_b128 v[168:171], v5 offset:37120
	ds_read_b128 v[172:175], v5 offset:37376
	ds_read_b128 v[176:179], v5 offset:37632
	ds_read_b128 v[180:183], v5 offset:37888
	ds_read_b32 v184, v9 offset:36864
	v_add_f32_dpp v145, v145, v145 quad_perm:[1,0,3,2] row_mask:0xf bank_mask:0xf bound_ctrl:1
	v_mul_f32 v153, v2, v202
	v_fma_f32 v153, v13, v203, v153
	v_add_f32_dpp v145, v145, v145 quad_perm:[2,3,0,1] row_mask:0xf bank_mask:0xf bound_ctrl:1
	v_fma_f32 v153, v12, v204, v153
	v_fma_f32 v153, v8, v205, v153
	v_add_f32_dpp v145, v145, v145 row_half_mirror row_mask:0xf bank_mask:0xf bound_ctrl:1
	v_mul_f32 v139, v228, v222
	v_mul_f32 v140, v228, v223
	v_add_f32_dpp v145, v145, v145 row_mirror row_mask:0xf bank_mask:0xf bound_ctrl:1
	v_fma_f32 v137, -v145, v212, v137
	v_fma_f32 v138, -v145, v213, v138
	v_fma_f32 v139, -v145, v214, v139
	v_fma_f32 v140, -v145, v215, v140
	v_fma_f32 v2, v2, v216, v137
	v_fma_f32 v13, v13, v217, v138
	v_fma_f32 v12, v12, v218, v139
	v_fma_f32 v8, v8, v219, v140
	s_waitcnt lgkmcnt(6)
	v_mul_f32 v137, v250, v242
	v_mul_f32 v138, v250, v243
	v_mul_f32 v145, v2, v230
	v_fma_f32 v145, v13, v231, v145
	v_fma_f32 v145, v12, v232, v145
	v_fma_f32 v145, v8, v233, v145
	ds_read_b128 v[186:189], v5 offset:38400
	ds_read_b128 v[190:193], v5 offset:38656
	ds_read_b128 v[194:197], v5 offset:38912
	ds_read_b128 v[198:201], v5 offset:39168
	ds_read_b128 v[202:205], v5 offset:39424
	ds_read_b32 v206, v9 offset:38400
	v_add_f32_dpp v145, v145, v145 quad_perm:[1,0,3,2] row_mask:0xf bank_mask:0xf bound_ctrl:1
	v_mul_f32 v154, v2, v224
	v_fma_f32 v154, v13, v225, v154
	v_add_f32_dpp v145, v145, v145 quad_perm:[2,3,0,1] row_mask:0xf bank_mask:0xf bound_ctrl:1
	v_fma_f32 v154, v12, v226, v154
	v_fma_f32 v154, v8, v227, v154
	v_add_f32_dpp v145, v145, v145 row_half_mirror row_mask:0xf bank_mask:0xf bound_ctrl:1
	v_mul_f32 v139, v250, v244
	v_mul_f32 v140, v250, v245
	v_add_f32_dpp v145, v145, v145 row_mirror row_mask:0xf bank_mask:0xf bound_ctrl:1
	v_fma_f32 v137, -v145, v234, v137
	v_fma_f32 v138, -v145, v235, v138
	v_fma_f32 v139, -v145, v236, v139
	v_fma_f32 v140, -v145, v237, v140
	v_fma_f32 v2, v2, v238, v137
	v_fma_f32 v13, v13, v239, v138
	v_fma_f32 v12, v12, v240, v139
	v_fma_f32 v8, v8, v241, v140
	s_waitcnt lgkmcnt(6)
	v_mul_f32 v137, v184, v176
	v_mul_f32 v138, v184, v177
	v_mul_f32 v145, v2, v164
	v_fma_f32 v145, v13, v165, v145
	v_fma_f32 v145, v12, v166, v145
	v_fma_f32 v145, v8, v167, v145
	ds_read_b128 v[208:211], v5 offset:39936
	ds_read_b128 v[212:215], v5 offset:40192
	ds_read_b128 v[216:219], v5 offset:40448
	ds_read_b128 v[220:223], v5 offset:40704
	ds_read_b128 v[224:227], v5 offset:40960
	ds_read_b32 v228, v9 offset:39936
	v_add_f32_dpp v145, v145, v145 quad_perm:[1,0,3,2] row_mask:0xf bank_mask:0xf bound_ctrl:1
	v_mul_f32 v155, v2, v246
	v_fma_f32 v155, v13, v247, v155
	v_add_f32_dpp v145, v145, v145 quad_perm:[2,3,0,1] row_mask:0xf bank_mask:0xf bound_ctrl:1
	v_fma_f32 v155, v12, v248, v155
	v_fma_f32 v155, v8, v249, v155
	v_add_f32_dpp v145, v145, v145 row_half_mirror row_mask:0xf bank_mask:0xf bound_ctrl:1
	v_mul_f32 v139, v184, v178
	v_mul_f32 v140, v184, v179
	v_add_f32_dpp v145, v145, v145 row_mirror row_mask:0xf bank_mask:0xf bound_ctrl:1
	v_fma_f32 v137, -v145, v168, v137
	v_fma_f32 v138, -v145, v169, v138
	v_fma_f32 v139, -v145, v170, v139
	v_fma_f32 v140, -v145, v171, v140
	v_fma_f32 v2, v2, v172, v137
	v_fma_f32 v13, v13, v173, v138
	v_fma_f32 v12, v12, v174, v139
	v_fma_f32 v8, v8, v175, v140
	s_waitcnt lgkmcnt(6)
	v_mul_f32 v137, v206, v198
	v_mul_f32 v138, v206, v199
	v_mul_f32 v145, v2, v186
	v_fma_f32 v145, v13, v187, v145
	v_fma_f32 v145, v12, v188, v145
	v_fma_f32 v145, v8, v189, v145
	ds_read_b128 v[230:233], v5 offset:41472
	ds_read_b128 v[234:237], v5 offset:41728
	ds_read_b128 v[238:241], v5 offset:41984
	ds_read_b128 v[242:245], v5 offset:42240
	ds_read_b128 v[246:249], v5 offset:42496
	ds_read_b32 v250, v9 offset:41472
	v_add_f32_dpp v145, v145, v145 quad_perm:[1,0,3,2] row_mask:0xf bank_mask:0xf bound_ctrl:1
	v_mul_f32 v156, v2, v180
	v_fma_f32 v156, v13, v181, v156
	v_add_f32_dpp v145, v145, v145 quad_perm:[2,3,0,1] row_mask:0xf bank_mask:0xf bound_ctrl:1
	v_fma_f32 v156, v12, v182, v156
	v_fma_f32 v156, v8, v183, v156
	v_add_f32_dpp v145, v145, v145 row_half_mirror row_mask:0xf bank_mask:0xf bound_ctrl:1
	v_mul_f32 v139, v206, v200
	v_mul_f32 v140, v206, v201
	v_add_f32_dpp v145, v145, v145 row_mirror row_mask:0xf bank_mask:0xf bound_ctrl:1
	v_fma_f32 v137, -v145, v190, v137
	v_fma_f32 v138, -v145, v191, v138
	v_fma_f32 v139, -v145, v192, v139
	v_fma_f32 v140, -v145, v193, v140
	v_fma_f32 v2, v2, v194, v137
	v_fma_f32 v13, v13, v195, v138
	v_fma_f32 v12, v12, v196, v139
	v_fma_f32 v8, v8, v197, v140
	s_waitcnt lgkmcnt(6)
	v_mul_f32 v137, v228, v220
	v_mul_f32 v138, v228, v221
	v_mul_f32 v145, v2, v208
	v_fma_f32 v145, v13, v209, v145
	v_fma_f32 v145, v12, v210, v145
	v_fma_f32 v145, v8, v211, v145
	ds_read_b128 v[164:167], v5 offset:43008
	ds_read_b128 v[168:171], v5 offset:43264
	ds_read_b128 v[172:175], v5 offset:43520
	ds_read_b128 v[176:179], v5 offset:43776
	ds_read_b128 v[180:183], v5 offset:44032
	ds_read_b32 v184, v9 offset:43008
	v_add_f32_dpp v145, v145, v145 quad_perm:[1,0,3,2] row_mask:0xf bank_mask:0xf bound_ctrl:1
	v_mul_f32 v157, v2, v202
	v_fma_f32 v157, v13, v203, v157
	v_add_f32_dpp v145, v145, v145 quad_perm:[2,3,0,1] row_mask:0xf bank_mask:0xf bound_ctrl:1
	v_fma_f32 v157, v12, v204, v157
	v_fma_f32 v157, v8, v205, v157
	v_add_f32_dpp v145, v145, v145 row_half_mirror row_mask:0xf bank_mask:0xf bound_ctrl:1
	v_mul_f32 v139, v228, v222
	v_mul_f32 v140, v228, v223
	v_add_f32_dpp v145, v145, v145 row_mirror row_mask:0xf bank_mask:0xf bound_ctrl:1
	v_fma_f32 v137, -v145, v212, v137
	v_fma_f32 v138, -v145, v213, v138
	v_fma_f32 v139, -v145, v214, v139
	v_fma_f32 v140, -v145, v215, v140
	v_fma_f32 v2, v2, v216, v137
	v_fma_f32 v13, v13, v217, v138
	v_fma_f32 v12, v12, v218, v139
	v_fma_f32 v8, v8, v219, v140
	s_waitcnt lgkmcnt(6)
	v_mul_f32 v137, v250, v242
	v_mul_f32 v138, v250, v243
	v_mul_f32 v145, v2, v230
	v_fma_f32 v145, v13, v231, v145
	v_fma_f32 v145, v12, v232, v145
	v_fma_f32 v145, v8, v233, v145
	ds_read_b128 v[186:189], v5 offset:44544
	ds_read_b128 v[190:193], v5 offset:44800
	ds_read_b128 v[194:197], v5 offset:45056
	ds_read_b128 v[198:201], v5 offset:45312
	ds_read_b128 v[202:205], v5 offset:45568
	ds_read_b32 v206, v9 offset:44544
	v_add_f32_dpp v145, v145, v145 quad_perm:[1,0,3,2] row_mask:0xf bank_mask:0xf bound_ctrl:1
	v_mul_f32 v158, v2, v224
	v_fma_f32 v158, v13, v225, v158
	v_add_f32_dpp v145, v145, v145 quad_perm:[2,3,0,1] row_mask:0xf bank_mask:0xf bound_ctrl:1
	v_fma_f32 v158, v12, v226, v158
	v_fma_f32 v158, v8, v227, v158
	v_add_f32_dpp v145, v145, v145 row_half_mirror row_mask:0xf bank_mask:0xf bound_ctrl:1
	v_mul_f32 v139, v250, v244
	v_mul_f32 v140, v250, v245
	v_add_f32_dpp v145, v145, v145 row_mirror row_mask:0xf bank_mask:0xf bound_ctrl:1
	v_fma_f32 v137, -v145, v234, v137
	v_fma_f32 v138, -v145, v235, v138
	v_fma_f32 v139, -v145, v236, v139
	v_fma_f32 v140, -v145, v237, v140
	v_fma_f32 v2, v2, v238, v137
	v_fma_f32 v13, v13, v239, v138
	v_fma_f32 v12, v12, v240, v139
	v_fma_f32 v8, v8, v241, v140
	s_waitcnt lgkmcnt(6)
	v_mul_f32 v137, v184, v176
	v_mul_f32 v138, v184, v177
	v_mul_f32 v145, v2, v164
	v_fma_f32 v145, v13, v165, v145
	v_fma_f32 v145, v12, v166, v145
	v_fma_f32 v145, v8, v167, v145
	ds_read_b128 v[208:211], v5 offset:46080
	ds_read_b128 v[212:215], v5 offset:46336
	ds_read_b128 v[216:219], v5 offset:46592
	ds_read_b128 v[220:223], v5 offset:46848
	ds_read_b128 v[224:227], v5 offset:47104
	ds_read_b32 v228, v9 offset:46080
	v_add_f32_dpp v145, v145, v145 quad_perm:[1,0,3,2] row_mask:0xf bank_mask:0xf bound_ctrl:1
	v_mul_f32 v159, v2, v246
	v_fma_f32 v159, v13, v247, v159
	v_add_f32_dpp v145, v145, v145 quad_perm:[2,3,0,1] row_mask:0xf bank_mask:0xf bound_ctrl:1
	v_fma_f32 v159, v12, v248, v159
	v_fma_f32 v159, v8, v249, v159
	v_add_f32_dpp v145, v145, v145 row_half_mirror row_mask:0xf bank_mask:0xf bound_ctrl:1
	v_mul_f32 v139, v184, v178
	v_mul_f32 v140, v184, v179
	v_add_f32_dpp v145, v145, v145 row_mirror row_mask:0xf bank_mask:0xf bound_ctrl:1
	v_fma_f32 v137, -v145, v168, v137
	v_fma_f32 v138, -v145, v169, v138
	v_fma_f32 v139, -v145, v170, v139
	v_fma_f32 v140, -v145, v171, v140
	v_fma_f32 v2, v2, v172, v137
	v_fma_f32 v13, v13, v173, v138
	v_fma_f32 v12, v12, v174, v139
	v_fma_f32 v8, v8, v175, v140
	s_waitcnt lgkmcnt(6)
	v_mul_f32 v137, v206, v198
	v_mul_f32 v138, v206, v199
	v_mul_f32 v145, v2, v186
	v_fma_f32 v145, v13, v187, v145
	v_fma_f32 v145, v12, v188, v145
	v_fma_f32 v145, v8, v189, v145
	ds_read_b128 v[230:233], v5 offset:47616
	ds_read_b128 v[234:237], v5 offset:47872
	ds_read_b128 v[238:241], v5 offset:48128
	ds_read_b128 v[242:245], v5 offset:48384
	ds_read_b128 v[246:249], v5 offset:48640
	ds_read_b32 v250, v9 offset:47616
	v_add_f32_dpp v145, v145, v145 quad_perm:[1,0,3,2] row_mask:0xf bank_mask:0xf bound_ctrl:1
	v_mul_f32 v160, v2, v180
	v_fma_f32 v160, v13, v181, v160
	v_add_f32_dpp v145, v145, v145 quad_perm:[2,3,0,1] row_mask:0xf bank_mask:0xf bound_ctrl:1
	v_fma_f32 v160, v12, v182, v160
	v_fma_f32 v160, v8, v183, v160
	v_add_f32_dpp v145, v145, v145 row_half_mirror row_mask:0xf bank_mask:0xf bound_ctrl:1
	v_mul_f32 v139, v206, v200
	v_mul_f32 v140, v206, v201
	v_add_f32_dpp v145, v145, v145 row_mirror row_mask:0xf bank_mask:0xf bound_ctrl:1
	v_fma_f32 v137, -v145, v190, v137
	v_fma_f32 v138, -v145, v191, v138
	v_fma_f32 v139, -v145, v192, v139
	v_fma_f32 v140, -v145, v193, v140
	v_fma_f32 v2, v2, v194, v137
	v_fma_f32 v13, v13, v195, v138
	v_fma_f32 v12, v12, v196, v139
	v_fma_f32 v8, v8, v197, v140
	s_waitcnt lgkmcnt(6)
	v_mul_f32 v137, v228, v220
	v_mul_f32 v138, v228, v221
	v_mul_f32 v145, v2, v208
	v_fma_f32 v145, v13, v209, v145
	v_fma_f32 v145, v12, v210, v145
	v_fma_f32 v145, v8, v211, v145
	s_nop 1
	v_add_f32_dpp v145, v145, v145 quad_perm:[1,0,3,2] row_mask:0xf bank_mask:0xf bound_ctrl:1
	v_mul_f32 v161, v2, v202
	v_fma_f32 v161, v13, v203, v161
	v_add_f32_dpp v145, v145, v145 quad_perm:[2,3,0,1] row_mask:0xf bank_mask:0xf bound_ctrl:1
	v_fma_f32 v161, v12, v204, v161
	v_fma_f32 v161, v8, v205, v161
	v_add_f32_dpp v145, v145, v145 row_half_mirror row_mask:0xf bank_mask:0xf bound_ctrl:1
	v_mul_f32 v139, v228, v222
	v_mul_f32 v140, v228, v223
	v_add_f32_dpp v145, v145, v145 row_mirror row_mask:0xf bank_mask:0xf bound_ctrl:1
	v_fma_f32 v137, -v145, v212, v137
	v_fma_f32 v138, -v145, v213, v138
	v_fma_f32 v139, -v145, v214, v139
	v_fma_f32 v140, -v145, v215, v140
	v_fma_f32 v2, v2, v216, v137
	v_fma_f32 v13, v13, v217, v138
	v_fma_f32 v12, v12, v218, v139
	v_fma_f32 v8, v8, v219, v140
	s_waitcnt lgkmcnt(0)
	v_mul_f32 v137, v250, v242
	v_mul_f32 v138, v250, v243
	v_mul_f32 v145, v2, v230
	v_fma_f32 v145, v13, v231, v145
	v_fma_f32 v145, v12, v232, v145
	v_fma_f32 v145, v8, v233, v145
	s_nop 1
	v_add_f32_dpp v145, v145, v145 quad_perm:[1,0,3,2] row_mask:0xf bank_mask:0xf bound_ctrl:1
	v_mul_f32 v162, v2, v224
	v_fma_f32 v162, v13, v225, v162
	v_add_f32_dpp v145, v145, v145 quad_perm:[2,3,0,1] row_mask:0xf bank_mask:0xf bound_ctrl:1
	v_fma_f32 v162, v12, v226, v162
	v_fma_f32 v162, v8, v227, v162
	v_add_f32_dpp v145, v145, v145 row_half_mirror row_mask:0xf bank_mask:0xf bound_ctrl:1
	v_mul_f32 v139, v250, v244
	v_mul_f32 v140, v250, v245
	v_add_f32_dpp v145, v145, v145 row_mirror row_mask:0xf bank_mask:0xf bound_ctrl:1
	v_fma_f32 v137, -v145, v234, v137
	v_fma_f32 v138, -v145, v235, v138
	v_fma_f32 v139, -v145, v236, v139
	v_fma_f32 v140, -v145, v237, v140
	v_fma_f32 v2, v2, v238, v137
	v_fma_f32 v13, v13, v239, v138
	v_fma_f32 v12, v12, v240, v139
	v_fma_f32 v8, v8, v241, v140
	v_mul_f32 v163, v2, v246
	v_fma_f32 v163, v13, v247, v163
	v_fma_f32 v163, v12, v248, v163
	v_fma_f32 v163, v8, v249, v163
	s_nop 0
	v_and_b32 v244, 8, v3
	v_cmp_ne_u32 vcc, 0, v244
	v_cndmask_b32 v244, v156, v148, vcc
	v_cndmask_b32 v245, v157, v149, vcc
	v_cndmask_b32 v246, v158, v150, vcc
	v_cndmask_b32 v247, v159, v151, vcc
	v_cndmask_b32 v230, v148, v156, vcc
	v_cndmask_b32 v231, v149, v157, vcc
	v_cndmask_b32 v232, v150, v158, vcc
	v_cndmask_b32 v233, v151, v159, vcc
	v_add_f32_dpp v230, v244, v230 row_mirror row_mask:0xf bank_mask:0xf bound_ctrl:1
	v_add_f32_dpp v231, v245, v231 row_mirror row_mask:0xf bank_mask:0xf bound_ctrl:1
	v_add_f32_dpp v232, v246, v232 row_mirror row_mask:0xf bank_mask:0xf bound_ctrl:1
	v_add_f32_dpp v233, v247, v233 row_mirror row_mask:0xf bank_mask:0xf bound_ctrl:1
	v_cndmask_b32 v244, v160, v152, vcc
	v_cndmask_b32 v245, v161, v153, vcc
	v_cndmask_b32 v246, v162, v154, vcc
	v_cndmask_b32 v247, v163, v155, vcc
	v_cndmask_b32 v234, v152, v160, vcc
	v_cndmask_b32 v235, v153, v161, vcc
	v_cndmask_b32 v236, v154, v162, vcc
	v_cndmask_b32 v237, v155, v163, vcc
	v_add_f32_dpp v234, v244, v234 row_mirror row_mask:0xf bank_mask:0xf bound_ctrl:1
	v_add_f32_dpp v235, v245, v235 row_mirror row_mask:0xf bank_mask:0xf bound_ctrl:1
	v_add_f32_dpp v236, v246, v236 row_mirror row_mask:0xf bank_mask:0xf bound_ctrl:1
	v_add_f32_dpp v237, v247, v237 row_mirror row_mask:0xf bank_mask:0xf bound_ctrl:1
	v_and_b32 v244, 4, v3
	v_cmp_ne_u32 vcc, 0, v244
	v_cndmask_b32 v244, v234, v230, vcc
	v_cndmask_b32 v245, v235, v231, vcc
	v_cndmask_b32 v246, v236, v232, vcc
	v_cndmask_b32 v247, v237, v233, vcc
	v_cndmask_b32 v238, v230, v234, vcc
	v_cndmask_b32 v239, v231, v235, vcc
	v_cndmask_b32 v240, v232, v236, vcc
	v_cndmask_b32 v241, v233, v237, vcc
	v_add_f32_dpp v238, v244, v238 row_half_mirror row_mask:0xf bank_mask:0xf bound_ctrl:1
	v_add_f32_dpp v239, v245, v239 row_half_mirror row_mask:0xf bank_mask:0xf bound_ctrl:1
	v_add_f32_dpp v240, v246, v240 row_half_mirror row_mask:0xf bank_mask:0xf bound_ctrl:1
	v_add_f32_dpp v241, v247, v241 row_half_mirror row_mask:0xf bank_mask:0xf bound_ctrl:1
	v_and_b32 v244, 2, v3
	v_cmp_ne_u32 vcc, 0, v244
	v_cndmask_b32 v244, v240, v238, vcc
	v_cndmask_b32 v245, v241, v239, vcc
	v_cndmask_b32 v242, v238, v240, vcc
	v_cndmask_b32 v243, v239, v241, vcc
	v_add_f32_dpp v242, v244, v242 quad_perm:[2,3,0,1] row_mask:0xf bank_mask:0xf bound_ctrl:1
	v_add_f32_dpp v243, v245, v243 quad_perm:[2,3,0,1] row_mask:0xf bank_mask:0xf bound_ctrl:1
	v_and_b32 v244, 1, v3
	v_cmp_ne_u32 vcc, 0, v244
	v_cndmask_b32 v244, v243, v242, vcc
	v_cndmask_b32 v245, v242, v243, vcc
	s_nop 0
	v_add_f32_dpp v19, v244, v245 quad_perm:[1,0,3,2] row_mask:0xf bank_mask:0xf bound_ctrl:1

; #define SCAN_BAR() asm volatile("s_barrier" ::: "memory")
; __device__ __forceinline__ void scan_unit(const Ctx& C0, const float* scn, int T, int quarter, const float* S0, float* Sout, unsigned char* obase, int mode) {
;     ...
;             if (mode == 0) { *(float*)(obase + (size_t)(k * 32 + q) * UPITCH_B + rl * 4) = osel0; *(float*)(obase + (size_t)(k * 32 + 16 + q) * UPITCH_B + rl * 4) = osel1; }
;             SCAN_BAR();
	v_lshl_add_u64 v[14:15], v[6:7], 0, s[0:1]
	v_add_co_u32_e32 v16, vcc, 0xfc29000, v14
	s_mov_b32 s8, 0xfc7f000
	s_nop 0
	v_addc_co_u32_e32 v17, vcc, 0, v15, vcc
	global_store_dword v[16:17], v18, off offset:768
	v_add_co_u32_e32 v16, vcc, 0xfc54000, v14
	s_add_u32 s0, s0, 0xac000
	s_nop 0
	v_addc_co_u32_e32 v17, vcc, 0, v15, vcc
	global_store_dword v[16:17], v19, off offset:768
	s_barrier
	ds_read_b128 v[164:167], v10 offset:0
	ds_read_b128 v[168:171], v10 offset:256
	ds_read_b128 v[172:175], v10 offset:512
	ds_read_b128 v[176:179], v10 offset:768
	ds_read_b128 v[180:183], v10 offset:1024
	ds_read_b32 v184, v11 offset:0
	ds_read_b128 v[186:189], v10 offset:1536
	ds_read_b128 v[190:193], v10 offset:1792
	ds_read_b128 v[194:197], v10 offset:2048
	ds_read_b128 v[198:201], v10 offset:2304
	ds_read_b128 v[202:205], v10 offset:2560
	ds_read_b32 v206, v11 offset:1536
	s_waitcnt lgkmcnt(0)
	v_mul_f32 v137, v184, v176
	v_mul_f32 v138, v184, v177
	v_mul_f32 v145, v2, v164
	v_fma_f32 v145, v13, v165, v145
	v_fma_f32 v145, v12, v166, v145
	v_fma_f32 v145, v8, v167, v145
	ds_read_b128 v[208:211], v10 offset:3072
	ds_read_b128 v[212:215], v10 offset:3328
	ds_read_b128 v[216:219], v10 offset:3584
	ds_read_b128 v[220:223], v10 offset:3840
	ds_read_b128 v[224:227], v10 offset:4096
	ds_read_b32 v228, v11 offset:3072
	v_add_f32_dpp v145, v145, v145 quad_perm:[1,0,3,2] row_mask:0xf bank_mask:0xf bound_ctrl:1
	s_nop 0
	s_nop 0
	v_add_f32_dpp v145, v145, v145 quad_perm:[2,3,0,1] row_mask:0xf bank_mask:0xf bound_ctrl:1
	s_nop 0
	s_nop 0
	v_add_f32_dpp v145, v145, v145 row_half_mirror row_mask:0xf bank_mask:0xf bound_ctrl:1
	v_mul_f32 v139, v184, v178
	v_mul_f32 v140, v184, v179
	v_add_f32_dpp v145, v145, v145 row_mirror row_mask:0xf bank_mask:0xf bound_ctrl:1
	v_fma_f32 v137, -v145, v168, v137
	v_fma_f32 v138, -v145, v169, v138
	v_fma_f32 v139, -v145, v170, v139
	v_fma_f32 v140, -v145, v171, v140
	v_fma_f32 v2, v2, v172, v137
	v_fma_f32 v13, v13, v173, v138
	v_fma_f32 v12, v12, v174, v139
	v_fma_f32 v8, v8, v175, v140
	s_waitcnt lgkmcnt(6)
	v_mul_f32 v137, v206, v198
	v_mul_f32 v138, v206, v199
	v_mul_f32 v145, v2, v186
	v_fma_f32 v145, v13, v187, v145
	v_fma_f32 v145, v12, v188, v145
	v_fma_f32 v145, v8, v189, v145
	ds_read_b128 v[230:233], v10 offset:4608
	ds_read_b128 v[234:237], v10 offset:4864
	ds_read_b128 v[238:241], v10 offset:5120
	ds_read_b128 v[242:245], v10 offset:5376
	ds_read_b128 v[246:249], v10 offset:5632
	ds_read_b32 v250, v11 offset:4608
	v_add_f32_dpp v145, v145, v145 quad_perm:[1,0,3,2] row_mask:0xf bank_mask:0xf bound_ctrl:1
	v_mul_f32 v148, v2, v180
	v_fma_f32 v148, v13, v181, v148
	v_add_f32_dpp v145, v145, v145 quad_perm:[2,3,0,1] row_mask:0xf bank_mask:0xf bound_ctrl:1
	v_fma_f32 v148, v12, v182, v148
	v_fma_f32 v148, v8, v183, v148
	v_add_f32_dpp v145, v145, v145 row_half_mirror row_mask:0xf bank_mask:0xf bound_ctrl:1
	v_mul_f32 v139, v206, v200
	v_mul_f32 v140, v206, v201
	v_add_f32_dpp v145, v145, v145 row_mirror row_mask:0xf bank_mask:0xf bound_ctrl:1
	v_fma_f32 v137, -v145, v190, v137
	v_fma_f32 v138, -v145, v191, v138
	v_fma_f32 v139, -v145, v192, v139
	v_fma_f32 v140, -v145, v193, v140
	v_fma_f32 v2, v2, v194, v137
	v_fma_f32 v13, v13, v195, v138
	v_fma_f32 v12, v12, v196, v139
	v_fma_f32 v8, v8, v197, v140
	s_waitcnt lgkmcnt(6)
	v_mul_f32 v137, v228, v220
	v_mul_f32 v138, v228, v221
	v_mul_f32 v145, v2, v208
	v_fma_f32 v145, v13, v209, v145
	v_fma_f32 v145, v12, v210, v145
	v_fma_f32 v145, v8, v211, v145
	ds_read_b128 v[164:167], v10 offset:6144
	ds_read_b128 v[168:171], v10 offset:6400
	ds_read_b128 v[172:175], v10 offset:6656
	ds_read_b128 v[176:179], v10 offset:6912
	ds_read_b128 v[180:183], v10 offset:7168
	ds_read_b32 v184, v11 offset:6144
	v_add_f32_dpp v145, v145, v145 quad_perm:[1,0,3,2] row_mask:0xf bank_mask:0xf bound_ctrl:1
	v_mul_f32 v149, v2, v202
	v_fma_f32 v149, v13, v203, v149
	v_add_f32_dpp v145, v145, v145 quad_perm:[2,3,0,1] row_mask:0xf bank_mask:0xf bound_ctrl:1
	v_fma_f32 v149, v12, v204, v149
	v_fma_f32 v149, v8, v205, v149
	v_add_f32_dpp v145, v145, v145 row_half_mirror row_mask:0xf bank_mask:0xf bound_ctrl:1
	v_mul_f32 v139, v228, v222
	v_mul_f32 v140, v228, v223
	v_add_f32_dpp v145, v145, v145 row_mirror row_mask:0xf bank_mask:0xf bound_ctrl:1
	v_fma_f32 v137, -v145, v212, v137
	v_fma_f32 v138, -v145, v213, v138
	v_fma_f32 v139, -v145, v214, v139
	v_fma_f32 v140, -v145, v215, v140
	v_fma_f32 v2, v2, v216, v137
	v_fma_f32 v13, v13, v217, v138
	v_fma_f32 v12, v12, v218, v139
	v_fma_f32 v8, v8, v219, v140
	s_waitcnt lgkmcnt(6)
	v_mul_f32 v137, v250, v242
	v_mul_f32 v138, v250, v243
	v_mul_f32 v145, v2, v230
	v_fma_f32 v145, v13, v231, v145
	v_fma_f32 v145, v12, v232, v145
	v_fma_f32 v145, v8, v233, v145
	ds_read_b128 v[186:189], v10 offset:7680
	ds_read_b128 v[190:193], v10 offset:7936
	ds_read_b128 v[194:197], v10 offset:8192
	ds_read_b128 v[198:201], v10 offset:8448
	ds_read_b128 v[202:205], v10 offset:8704
	ds_read_b32 v206, v11 offset:7680
	v_add_f32_dpp v145, v145, v145 quad_perm:[1,0,3,2] row_mask:0xf bank_mask:0xf bound_ctrl:1
	v_mul_f32 v150, v2, v224
	v_fma_f32 v150, v13, v225, v150
	v_add_f32_dpp v145, v145, v145 quad_perm:[2,3,0,1] row_mask:0xf bank_mask:0xf bound_ctrl:1
	v_fma_f32 v150, v12, v226, v150
	v_fma_f32 v150, v8, v227, v150
	v_add_f32_dpp v145, v145, v145 row_half_mirror row_mask:0xf bank_mask:0xf bound_ctrl:1
	v_mul_f32 v139, v250, v244
	v_mul_f32 v140, v250, v245
	v_add_f32_dpp v145, v145, v145 row_mirror row_mask:0xf bank_mask:0xf bound_ctrl:1
	v_fma_f32 v137, -v145, v234, v137
	v_fma_f32 v138, -v145, v235, v138
	v_fma_f32 v139, -v145, v236, v139
	v_fma_f32 v140, -v145, v237, v140
	v_fma_f32 v2, v2, v238, v137
	v_fma_f32 v13, v13, v239, v138
	v_fma_f32 v12, v12, v240, v139
	v_fma_f32 v8, v8, v241, v140
	s_waitcnt lgkmcnt(6)
	v_mul_f32 v137, v184, v176
	v_mul_f32 v138, v184, v177
	v_mul_f32 v145, v2, v164
	v_fma_f32 v145, v13, v165, v145
	v_fma_f32 v145, v12, v166, v145
	v_fma_f32 v145, v8, v167, v145
	ds_read_b128 v[208:211], v10 offset:9216
	ds_read_b128 v[212:215], v10 offset:9472
	ds_read_b128 v[216:219], v10 offset:9728
	ds_read_b128 v[220:223], v10 offset:9984
	ds_read_b128 v[224:227], v10 offset:10240
	ds_read_b32 v228, v11 offset:9216
	v_add_f32_dpp v145, v145, v145 quad_perm:[1,0,3,2] row_mask:0xf bank_mask:0xf bound_ctrl:1
	v_mul_f32 v151, v2, v246
	v_fma_f32 v151, v13, v247, v151
	v_add_f32_dpp v145, v145, v145 quad_perm:[2,3,0,1] row_mask:0xf bank_mask:0xf bound_ctrl:1
	v_fma_f32 v151, v12, v248, v151
	v_fma_f32 v151, v8, v249, v151
	v_add_f32_dpp v145, v145, v145 row_half_mirror row_mask:0xf bank_mask:0xf bound_ctrl:1
	v_mul_f32 v139, v184, v178
	v_mul_f32 v140, v184, v179
	v_add_f32_dpp v145, v145, v145 row_mirror row_mask:0xf bank_mask:0xf bound_ctrl:1
	v_fma_f32 v137, -v145, v168, v137
	v_fma_f32 v138, -v145, v169, v138
	v_fma_f32 v139, -v145, v170, v139
	v_fma_f32 v140, -v145, v171, v140
	v_fma_f32 v2, v2, v172, v137
	v_fma_f32 v13, v13, v173, v138
	v_fma_f32 v12, v12, v174, v139
	v_fma_f32 v8, v8, v175, v140
	s_waitcnt lgkmcnt(6)
	v_mul_f32 v137, v206, v198
	v_mul_f32 v138, v206, v199
	v_mul_f32 v145, v2, v186
	v_fma_f32 v145, v13, v187, v145
	v_fma_f32 v145, v12, v188, v145
	v_fma_f32 v145, v8, v189, v145
	ds_read_b128 v[230:233], v10 offset:10752
	ds_read_b128 v[234:237], v10 offset:11008
	ds_read_b128 v[238:241], v10 offset:11264
	ds_read_b128 v[242:245], v10 offset:11520
	ds_read_b128 v[246:249], v10 offset:11776
	ds_read_b32 v250, v11 offset:10752
	v_add_f32_dpp v145, v145, v145 quad_perm:[1,0,3,2] row_mask:0xf bank_mask:0xf bound_ctrl:1
	v_mul_f32 v152, v2, v180
	v_fma_f32 v152, v13, v181, v152
	v_add_f32_dpp v145, v145, v145 quad_perm:[2,3,0,1] row_mask:0xf bank_mask:0xf bound_ctrl:1
	v_fma_f32 v152, v12, v182, v152
	v_fma_f32 v152, v8, v183, v152
	v_add_f32_dpp v145, v145, v145 row_half_mirror row_mask:0xf bank_mask:0xf bound_ctrl:1
	v_mul_f32 v139, v206, v200
	v_mul_f32 v140, v206, v201
	v_add_f32_dpp v145, v145, v145 row_mirror row_mask:0xf bank_mask:0xf bound_ctrl:1
	v_fma_f32 v137, -v145, v190, v137
	v_fma_f32 v138, -v145, v191, v138
	v_fma_f32 v139, -v145, v192, v139
	v_fma_f32 v140, -v145, v193, v140
	v_fma_f32 v2, v2, v194, v137
	v_fma_f32 v13, v13, v195, v138
	v_fma_f32 v12, v12, v196, v139
	v_fma_f32 v8, v8, v197, v140
	s_waitcnt lgkmcnt(6)
	v_mul_f32 v137, v228, v220
	v_mul_f32 v138, v228, v221
	v_mul_f32 v145, v2, v208
	v_fma_f32 v145, v13, v209, v145
	v_fma_f32 v145, v12, v210, v145
	v_fma_f32 v145, v8, v211, v145
	ds_read_b128 v[164:167], v10 offset:12288
	ds_read_b128 v[168:171], v10 offset:12544
	ds_read_b128 v[172:175], v10 offset:12800
	ds_read_b128 v[176:179], v10 offset:13056
	ds_read_b128 v[180:183], v10 offset:13312
	ds_read_b32 v184, v11 offset:12288
	v_add_f32_dpp v145, v145, v145 quad_perm:[1,0,3,2] row_mask:0xf bank_mask:0xf bound_ctrl:1
	v_mul_f32 v153, v2, v202
	v_fma_f32 v153, v13, v203, v153
	v_add_f32_dpp v145, v145, v145 quad_perm:[2,3,0,1] row_mask:0xf bank_mask:0xf bound_ctrl:1
	v_fma_f32 v153, v12, v204, v153
	v_fma_f32 v153, v8, v205, v153
	v_add_f32_dpp v145, v145, v145 row_half_mirror row_mask:0xf bank_mask:0xf bound_ctrl:1
	v_mul_f32 v139, v228, v222
	v_mul_f32 v140, v228, v223
	v_add_f32_dpp v145, v145, v145 row_mirror row_mask:0xf bank_mask:0xf bound_ctrl:1
	v_fma_f32 v137, -v145, v212, v137
	v_fma_f32 v138, -v145, v213, v138
	v_fma_f32 v139, -v145, v214, v139
	v_fma_f32 v140, -v145, v215, v140
	v_fma_f32 v2, v2, v216, v137
	v_fma_f32 v13, v13, v217, v138
	v_fma_f32 v12, v12, v218, v139
	v_fma_f32 v8, v8, v219, v140
	s_waitcnt lgkmcnt(6)
	v_mul_f32 v137, v250, v242
	v_mul_f32 v138, v250, v243
	v_mul_f32 v145, v2, v230
	v_fma_f32 v145, v13, v231, v145
	v_fma_f32 v145, v12, v232, v145
	v_fma_f32 v145, v8, v233, v145
	ds_read_b128 v[186:189], v10 offset:13824
	ds_read_b128 v[190:193], v10 offset:14080
	ds_read_b128 v[194:197], v10 offset:14336
	ds_read_b128 v[198:201], v10 offset:14592
	ds_read_b128 v[202:205], v10 offset:14848
	ds_read_b32 v206, v11 offset:13824
	v_add_f32_dpp v145, v145, v145 quad_perm:[1,0,3,2] row_mask:0xf bank_mask:0xf bound_ctrl:1
	v_mul_f32 v154, v2, v224
	v_fma_f32 v154, v13, v225, v154
	v_add_f32_dpp v145, v145, v145 quad_perm:[2,3,0,1] row_mask:0xf bank_mask:0xf bound_ctrl:1
	v_fma_f32 v154, v12, v226, v154
	v_fma_f32 v154, v8, v227, v154
	v_add_f32_dpp v145, v145, v145 row_half_mirror row_mask:0xf bank_mask:0xf bound_ctrl:1
	v_mul_f32 v139, v250, v244
	v_mul_f32 v140, v250, v245
	v_add_f32_dpp v145, v145, v145 row_mirror row_mask:0xf bank_mask:0xf bound_ctrl:1
	v_fma_f32 v137, -v145, v234, v137
	v_fma_f32 v138, -v145, v235, v138
	v_fma_f32 v139, -v145, v236, v139
	v_fma_f32 v140, -v145, v237, v140
	v_fma_f32 v2, v2, v238, v137
	v_fma_f32 v13, v13, v239, v138
	v_fma_f32 v12, v12, v240, v139
	v_fma_f32 v8, v8, v241, v140
	s_waitcnt lgkmcnt(6)
	v_mul_f32 v137, v184, v176
	v_mul_f32 v138, v184, v177
	v_mul_f32 v145, v2, v164
	v_fma_f32 v145, v13, v165, v145
	v_fma_f32 v145, v12, v166, v145
	v_fma_f32 v145, v8, v167, v145
	ds_read_b128 v[208:211], v10 offset:15360
	ds_read_b128 v[212:215], v10 offset:15616
	ds_read_b128 v[216:219], v10 offset:15872
	ds_read_b128 v[220:223], v10 offset:16128
	ds_read_b128 v[224:227], v10 offset:16384
	ds_read_b32 v228, v11 offset:15360
	v_add_f32_dpp v145, v145, v145 quad_perm:[1,0,3,2] row_mask:0xf bank_mask:0xf bound_ctrl:1
	v_mul_f32 v155, v2, v246
	v_fma_f32 v155, v13, v247, v155
	v_add_f32_dpp v145, v145, v145 quad_perm:[2,3,0,1] row_mask:0xf bank_mask:0xf bound_ctrl:1
	v_fma_f32 v155, v12, v248, v155
	v_fma_f32 v155, v8, v249, v155
	v_add_f32_dpp v145, v145, v145 row_half_mirror row_mask:0xf bank_mask:0xf bound_ctrl:1
	v_mul_f32 v139, v184, v178
	v_mul_f32 v140, v184, v179
	v_add_f32_dpp v145, v145, v145 row_mirror row_mask:0xf bank_mask:0xf bound_ctrl:1
	v_fma_f32 v137, -v145, v168, v137
	v_fma_f32 v138, -v145, v169, v138
	v_fma_f32 v139, -v145, v170, v139
	v_fma_f32 v140, -v145, v171, v140
	v_fma_f32 v2, v2, v172, v137
	v_fma_f32 v13, v13, v173, v138
	v_fma_f32 v12, v12, v174, v139
	v_fma_f32 v8, v8, v175, v140
	s_waitcnt lgkmcnt(6)
	v_mul_f32 v137, v206, v198
	v_mul_f32 v138, v206, v199
	v_mul_f32 v145, v2, v186
	v_fma_f32 v145, v13, v187, v145
	v_fma_f32 v145, v12, v188, v145
	v_fma_f32 v145, v8, v189, v145
	ds_read_b128 v[230:233], v10 offset:16896
	ds_read_b128 v[234:237], v10 offset:17152
	ds_read_b128 v[238:241], v10 offset:17408
	ds_read_b128 v[242:245], v10 offset:17664
	ds_read_b128 v[246:249], v10 offset:17920
	ds_read_b32 v250, v11 offset:16896
	v_add_f32_dpp v145, v145, v145 quad_perm:[1,0,3,2] row_mask:0xf bank_mask:0xf bound_ctrl:1
	v_mul_f32 v156, v2, v180
	v_fma_f32 v156, v13, v181, v156
	v_add_f32_dpp v145, v145, v145 quad_perm:[2,3,0,1] row_mask:0xf bank_mask:0xf bound_ctrl:1
	v_fma_f32 v156, v12, v182, v156
	v_fma_f32 v156, v8, v183, v156
	v_add_f32_dpp v145, v145, v145 row_half_mirror row_mask:0xf bank_mask:0xf bound_ctrl:1
	v_mul_f32 v139, v206, v200
	v_mul_f32 v140, v206, v201
	v_add_f32_dpp v145, v145, v145 row_mirror row_mask:0xf bank_mask:0xf bound_ctrl:1
	v_fma_f32 v137, -v145, v190, v137
	v_fma_f32 v138, -v145, v191, v138
	v_fma_f32 v139, -v145, v192, v139
	v_fma_f32 v140, -v145, v193, v140
	v_fma_f32 v2, v2, v194, v137
	v_fma_f32 v13, v13, v195, v138
	v_fma_f32 v12, v12, v196, v139
	v_fma_f32 v8, v8, v197, v140
	s_waitcnt lgkmcnt(6)
	v_mul_f32 v137, v228, v220
	v_mul_f32 v138, v228, v221
	v_mul_f32 v145, v2, v208
	v_fma_f32 v145, v13, v209, v145
	v_fma_f32 v145, v12, v210, v145
	v_fma_f32 v145, v8, v211, v145
	ds_read_b128 v[164:167], v10 offset:18432
	ds_read_b128 v[168:171], v10 offset:18688
	ds_read_b128 v[172:175], v10 offset:18944
	ds_read_b128 v[176:179], v10 offset:19200
	ds_read_b128 v[180:183], v10 offset:19456
	ds_read_b32 v184, v11 offset:18432
	v_add_f32_dpp v145, v145, v145 quad_perm:[1,0,3,2] row_mask:0xf bank_mask:0xf bound_ctrl:1
	v_mul_f32 v157, v2, v202
	v_fma_f32 v157, v13, v203, v157
	v_add_f32_dpp v145, v145, v145 quad_perm:[2,3,0,1] row_mask:0xf bank_mask:0xf bound_ctrl:1
	v_fma_f32 v157, v12, v204, v157
	v_fma_f32 v157, v8, v205, v157
	v_add_f32_dpp v145, v145, v145 row_half_mirror row_mask:0xf bank_mask:0xf bound_ctrl:1
	v_mul_f32 v139, v228, v222
	v_mul_f32 v140, v228, v223
	v_add_f32_dpp v145, v145, v145 row_mirror row_mask:0xf bank_mask:0xf bound_ctrl:1
	v_fma_f32 v137, -v145, v212, v137
	v_fma_f32 v138, -v145, v213, v138
	v_fma_f32 v139, -v145, v214, v139
	v_fma_f32 v140, -v145, v215, v140
	v_fma_f32 v2, v2, v216, v137
	v_fma_f32 v13, v13, v217, v138
	v_fma_f32 v12, v12, v218, v139
	v_fma_f32 v8, v8, v219, v140
	s_waitcnt lgkmcnt(6)
	v_mul_f32 v137, v250, v242
	v_mul_f32 v138, v250, v243
	v_mul_f32 v145, v2, v230
	v_fma_f32 v145, v13, v231, v145
	v_fma_f32 v145, v12, v232, v145
	v_fma_f32 v145, v8, v233, v145
	ds_read_b128 v[186:189], v10 offset:19968
	ds_read_b128 v[190:193], v10 offset:20224
	ds_read_b128 v[194:197], v10 offset:20480
	ds_read_b128 v[198:201], v10 offset:20736
	ds_read_b128 v[202:205], v10 offset:20992
	ds_read_b32 v206, v11 offset:19968
	v_add_f32_dpp v145, v145, v145 quad_perm:[1,0,3,2] row_mask:0xf bank_mask:0xf bound_ctrl:1
	v_mul_f32 v158, v2, v224
	v_fma_f32 v158, v13, v225, v158
	v_add_f32_dpp v145, v145, v145 quad_perm:[2,3,0,1] row_mask:0xf bank_mask:0xf bound_ctrl:1
	v_fma_f32 v158, v12, v226, v158
	v_fma_f32 v158, v8, v227, v158
	v_add_f32_dpp v145, v145, v145 row_half_mirror row_mask:0xf bank_mask:0xf bound_ctrl:1
	v_mul_f32 v139, v250, v244
	v_mul_f32 v140, v250, v245
	v_add_f32_dpp v145, v145, v145 row_mirror row_mask:0xf bank_mask:0xf bound_ctrl:1
	v_fma_f32 v137, -v145, v234, v137
	v_fma_f32 v138, -v145, v235, v138
	v_fma_f32 v139, -v145, v236, v139
	v_fma_f32 v140, -v145, v237, v140
	v_fma_f32 v2, v2, v238, v137
	v_fma_f32 v13, v13, v239, v138
	v_fma_f32 v12, v12, v240, v139
	v_fma_f32 v8, v8, v241, v140
	s_waitcnt lgkmcnt(6)
	v_mul_f32 v137, v184, v176
	v_mul_f32 v138, v184, v177
	v_mul_f32 v145, v2, v164
	v_fma_f32 v145, v13, v165, v145
	v_fma_f32 v145, v12, v166, v145
	v_fma_f32 v145, v8, v167, v145
	ds_read_b128 v[208:211], v10 offset:21504
	ds_read_b128 v[212:215], v10 offset:21760
	ds_read_b128 v[216:219], v10 offset:22016
	ds_read_b128 v[220:223], v10 offset:22272
	ds_read_b128 v[224:227], v10 offset:22528
	ds_read_b32 v228, v11 offset:21504
	v_add_f32_dpp v145, v145, v145 quad_perm:[1,0,3,2] row_mask:0xf bank_mask:0xf bound_ctrl:1
	v_mul_f32 v159, v2, v246
	v_fma_f32 v159, v13, v247, v159
	v_add_f32_dpp v145, v145, v145 quad_perm:[2,3,0,1] row_mask:0xf bank_mask:0xf bound_ctrl:1
	v_fma_f32 v159, v12, v248, v159
	v_fma_f32 v159, v8, v249, v159
	v_add_f32_dpp v145, v145, v145 row_half_mirror row_mask:0xf bank_mask:0xf bound_ctrl:1
	v_mul_f32 v139, v184, v178
	v_mul_f32 v140, v184, v179
	v_add_f32_dpp v145, v145, v145 row_mirror row_mask:0xf bank_mask:0xf bound_ctrl:1
	v_fma_f32 v137, -v145, v168, v137
	v_fma_f32 v138, -v145, v169, v138
	v_fma_f32 v139, -v145, v170, v139
	v_fma_f32 v140, -v145, v171, v140
	v_fma_f32 v2, v2, v172, v137
	v_fma_f32 v13, v13, v173, v138
	v_fma_f32 v12, v12, v174, v139
	v_fma_f32 v8, v8, v175, v140
	s_waitcnt lgkmcnt(6)
	v_mul_f32 v137, v206, v198
	v_mul_f32 v138, v206, v199
	v_mul_f32 v145, v2, v186
	v_fma_f32 v145, v13, v187, v145
	v_fma_f32 v145, v12, v188, v145
	v_fma_f32 v145, v8, v189, v145
	ds_read_b128 v[230:233], v10 offset:23040
	ds_read_b128 v[234:237], v10 offset:23296
	ds_read_b128 v[238:241], v10 offset:23552
	ds_read_b128 v[242:245], v10 offset:23808
	ds_read_b128 v[246:249], v10 offset:24064
	ds_read_b32 v250, v11 offset:23040
	v_add_f32_dpp v145, v145, v145 quad_perm:[1,0,3,2] row_mask:0xf bank_mask:0xf bound_ctrl:1
	v_mul_f32 v160, v2, v180
	v_fma_f32 v160, v13, v181, v160
	v_add_f32_dpp v145, v145, v145 quad_perm:[2,3,0,1] row_mask:0xf bank_mask:0xf bound_ctrl:1
	v_fma_f32 v160, v12, v182, v160
	v_fma_f32 v160, v8, v183, v160
	v_add_f32_dpp v145, v145, v145 row_half_mirror row_mask:0xf bank_mask:0xf bound_ctrl:1
	v_mul_f32 v139, v206, v200
	v_mul_f32 v140, v206, v201
	v_add_f32_dpp v145, v145, v145 row_mirror row_mask:0xf bank_mask:0xf bound_ctrl:1
	v_fma_f32 v137, -v145, v190, v137
	v_fma_f32 v138, -v145, v191, v138
	v_fma_f32 v139, -v145, v192, v139
	v_fma_f32 v140, -v145, v193, v140
	v_fma_f32 v2, v2, v194, v137
	v_fma_f32 v13, v13, v195, v138
	v_fma_f32 v12, v12, v196, v139
	v_fma_f32 v8, v8, v197, v140
	s_waitcnt lgkmcnt(6)
	v_mul_f32 v137, v228, v220
	v_mul_f32 v138, v228, v221
	v_mul_f32 v145, v2, v208
	v_fma_f32 v145, v13, v209, v145
	v_fma_f32 v145, v12, v210, v145
	v_fma_f32 v145, v8, v211, v145
	ds_read_b128 v[164:167], v10 offset:24576
	ds_read_b128 v[168:171], v10 offset:24832
	ds_read_b128 v[172:175], v10 offset:25088
	ds_read_b128 v[176:179], v10 offset:25344
	ds_read_b128 v[180:183], v10 offset:25600
	ds_read_b32 v184, v11 offset:24576
	v_add_f32_dpp v145, v145, v145 quad_perm:[1,0,3,2] row_mask:0xf bank_mask:0xf bound_ctrl:1
	v_mul_f32 v161, v2, v202
	v_fma_f32 v161, v13, v203, v161
	v_add_f32_dpp v145, v145, v145 quad_perm:[2,3,0,1] row_mask:0xf bank_mask:0xf bound_ctrl:1
	v_fma_f32 v161, v12, v204, v161
	v_fma_f32 v161, v8, v205, v161
	v_add_f32_dpp v145, v145, v145 row_half_mirror row_mask:0xf bank_mask:0xf bound_ctrl:1
	v_mul_f32 v139, v228, v222
	v_mul_f32 v140, v228, v223
	v_add_f32_dpp v145, v145, v145 row_mirror row_mask:0xf bank_mask:0xf bound_ctrl:1
	v_fma_f32 v137, -v145, v212, v137
	v_fma_f32 v138, -v145, v213, v138
	v_fma_f32 v139, -v145, v214, v139
	v_fma_f32 v140, -v145, v215, v140
	v_fma_f32 v2, v2, v216, v137
	v_fma_f32 v13, v13, v217, v138
	v_fma_f32 v12, v12, v218, v139
	v_fma_f32 v8, v8, v219, v140
	s_waitcnt lgkmcnt(6)
	v_mul_f32 v137, v250, v242
	v_mul_f32 v138, v250, v243
	v_mul_f32 v145, v2, v230
	v_fma_f32 v145, v13, v231, v145
	v_fma_f32 v145, v12, v232, v145
	v_fma_f32 v145, v8, v233, v145
	ds_read_b128 v[186:189], v10 offset:26112
	ds_read_b128 v[190:193], v10 offset:26368
	ds_read_b128 v[194:197], v10 offset:26624
	ds_read_b128 v[198:201], v10 offset:26880
	ds_read_b128 v[202:205], v10 offset:27136
	ds_read_b32 v206, v11 offset:26112
	v_add_f32_dpp v145, v145, v145 quad_perm:[1,0,3,2] row_mask:0xf bank_mask:0xf bound_ctrl:1
	v_mul_f32 v162, v2, v224
	v_fma_f32 v162, v13, v225, v162
	v_add_f32_dpp v145, v145, v145 quad_perm:[2,3,0,1] row_mask:0xf bank_mask:0xf bound_ctrl:1
	v_fma_f32 v162, v12, v226, v162
	v_fma_f32 v162, v8, v227, v162
	v_add_f32_dpp v145, v145, v145 row_half_mirror row_mask:0xf bank_mask:0xf bound_ctrl:1
	v_mul_f32 v139, v250, v244
	v_mul_f32 v140, v250, v245
	v_add_f32_dpp v145, v145, v145 row_mirror row_mask:0xf bank_mask:0xf bound_ctrl:1
	v_fma_f32 v137, -v145, v234, v137
	v_fma_f32 v138, -v145, v235, v138
	v_fma_f32 v139, -v145, v236, v139
	v_fma_f32 v140, -v145, v237, v140
	v_fma_f32 v2, v2, v238, v137
	v_fma_f32 v13, v13, v239, v138
	v_fma_f32 v12, v12, v240, v139
	v_fma_f32 v8, v8, v241, v140
	s_waitcnt lgkmcnt(6)
	v_mul_f32 v137, v184, v176
	v_mul_f32 v138, v184, v177
	v_mul_f32 v145, v2, v164
	v_fma_f32 v145, v13, v165, v145
	v_fma_f32 v145, v12, v166, v145
	v_fma_f32 v145, v8, v167, v145
	ds_read_b128 v[208:211], v10 offset:27648
	ds_read_b128 v[212:215], v10 offset:27904
	ds_read_b128 v[216:219], v10 offset:28160
	ds_read_b128 v[220:223], v10 offset:28416
	ds_read_b128 v[224:227], v10 offset:28672
	ds_read_b32 v228, v11 offset:27648
	v_add_f32_dpp v145, v145, v145 quad_perm:[1,0,3,2] row_mask:0xf bank_mask:0xf bound_ctrl:1
	v_mul_f32 v163, v2, v246
	v_fma_f32 v163, v13, v247, v163
	v_add_f32_dpp v145, v145, v145 quad_perm:[2,3,0,1] row_mask:0xf bank_mask:0xf bound_ctrl:1
	v_fma_f32 v163, v12, v248, v163
	v_fma_f32 v163, v8, v249, v163
	v_add_f32_dpp v145, v145, v145 row_half_mirror row_mask:0xf bank_mask:0xf bound_ctrl:1
	v_mul_f32 v139, v184, v178
	v_mul_f32 v140, v184, v179
	v_add_f32_dpp v145, v145, v145 row_mirror row_mask:0xf bank_mask:0xf bound_ctrl:1
	v_fma_f32 v137, -v145, v168, v137
	v_fma_f32 v138, -v145, v169, v138
	v_fma_f32 v139, -v145, v170, v139
	v_fma_f32 v140, -v145, v171, v140
	v_fma_f32 v2, v2, v172, v137
	v_fma_f32 v13, v13, v173, v138
	v_fma_f32 v12, v12, v174, v139
	v_fma_f32 v8, v8, v175, v140
	s_waitcnt lgkmcnt(6)
	v_and_b32 v244, 8, v3
	v_cmp_ne_u32 vcc, 0, v244
	v_cndmask_b32 v244, v156, v148, vcc
	v_cndmask_b32 v245, v157, v149, vcc
	v_cndmask_b32 v246, v158, v150, vcc
	v_cndmask_b32 v247, v159, v151, vcc
	v_cndmask_b32 v230, v148, v156, vcc
	v_cndmask_b32 v231, v149, v157, vcc
	v_cndmask_b32 v232, v150, v158, vcc
	v_cndmask_b32 v233, v151, v159, vcc
	v_add_f32_dpp v230, v244, v230 row_mirror row_mask:0xf bank_mask:0xf bound_ctrl:1
	v_add_f32_dpp v231, v245, v231 row_mirror row_mask:0xf bank_mask:0xf bound_ctrl:1
	v_add_f32_dpp v232, v246, v232 row_mirror row_mask:0xf bank_mask:0xf bound_ctrl:1
	v_add_f32_dpp v233, v247, v233 row_mirror row_mask:0xf bank_mask:0xf bound_ctrl:1
	v_cndmask_b32 v244, v160, v152, vcc
	v_cndmask_b32 v245, v161, v153, vcc
	v_cndmask_b32 v246, v162, v154, vcc
	v_cndmask_b32 v247, v163, v155, vcc
	v_cndmask_b32 v234, v152, v160, vcc
	v_cndmask_b32 v235, v153, v161, vcc
	v_cndmask_b32 v236, v154, v162, vcc
	v_cndmask_b32 v237, v155, v163, vcc
	v_add_f32_dpp v234, v244, v234 row_mirror row_mask:0xf bank_mask:0xf bound_ctrl:1
	v_add_f32_dpp v235, v245, v235 row_mirror row_mask:0xf bank_mask:0xf bound_ctrl:1
	v_add_f32_dpp v236, v246, v236 row_mirror row_mask:0xf bank_mask:0xf bound_ctrl:1
	v_add_f32_dpp v237, v247, v237 row_mirror row_mask:0xf bank_mask:0xf bound_ctrl:1
	v_and_b32 v244, 4, v3
	v_cmp_ne_u32 vcc, 0, v244
	v_cndmask_b32 v244, v234, v230, vcc
	v_cndmask_b32 v245, v235, v231, vcc
	v_cndmask_b32 v246, v236, v232, vcc
	v_cndmask_b32 v247, v237, v233, vcc
	v_cndmask_b32 v238, v230, v234, vcc
	v_cndmask_b32 v239, v231, v235, vcc
	v_cndmask_b32 v240, v232, v236, vcc
	v_cndmask_b32 v241, v233, v237, vcc
	v_add_f32_dpp v238, v244, v238 row_half_mirror row_mask:0xf bank_mask:0xf bound_ctrl:1
	v_add_f32_dpp v239, v245, v239 row_half_mirror row_mask:0xf bank_mask:0xf bound_ctrl:1
	v_add_f32_dpp v240, v246, v240 row_half_mirror row_mask:0xf bank_mask:0xf bound_ctrl:1
	v_add_f32_dpp v241, v247, v241 row_half_mirror row_mask:0xf bank_mask:0xf bound_ctrl:1
	v_and_b32 v244, 2, v3
	v_cmp_ne_u32 vcc, 0, v244
	v_cndmask_b32 v244, v240, v238, vcc
	v_cndmask_b32 v245, v241, v239, vcc
	v_cndmask_b32 v242, v238, v240, vcc
	v_cndmask_b32 v243, v239, v241, vcc
	v_add_f32_dpp v242, v244, v242 quad_perm:[2,3,0,1] row_mask:0xf bank_mask:0xf bound_ctrl:1
	v_add_f32_dpp v243, v245, v243 quad_perm:[2,3,0,1] row_mask:0xf bank_mask:0xf bound_ctrl:1
	v_and_b32 v244, 1, v3
	v_cmp_ne_u32 vcc, 0, v244
	v_cndmask_b32 v244, v243, v242, vcc
	v_cndmask_b32 v245, v242, v243, vcc
	s_nop 0
	v_add_f32_dpp v18, v244, v245 quad_perm:[1,0,3,2] row_mask:0xf bank_mask:0xf bound_ctrl:1
	v_mul_f32 v137, v206, v198
	v_mul_f32 v138, v206, v199
	v_mul_f32 v145, v2, v186
	v_fma_f32 v145, v13, v187, v145
	v_fma_f32 v145, v12, v188, v145
	v_fma_f32 v145, v8, v189, v145
	ds_read_b128 v[230:233], v10 offset:29184
	ds_read_b128 v[234:237], v10 offset:29440
	ds_read_b128 v[238:241], v10 offset:29696
	ds_read_b128 v[242:245], v10 offset:29952
	ds_read_b128 v[246:249], v10 offset:30208
	ds_read_b32 v250, v11 offset:29184
	v_add_f32_dpp v145, v145, v145 quad_perm:[1,0,3,2] row_mask:0xf bank_mask:0xf bound_ctrl:1
	v_mul_f32 v148, v2, v180
	v_fma_f32 v148, v13, v181, v148
	v_add_f32_dpp v145, v145, v145 quad_perm:[2,3,0,1] row_mask:0xf bank_mask:0xf bound_ctrl:1
	v_fma_f32 v148, v12, v182, v148
	v_fma_f32 v148, v8, v183, v148
	v_add_f32_dpp v145, v145, v145 row_half_mirror row_mask:0xf bank_mask:0xf bound_ctrl:1
	v_mul_f32 v139, v206, v200
	v_mul_f32 v140, v206, v201
	v_add_f32_dpp v145, v145, v145 row_mirror row_mask:0xf bank_mask:0xf bound_ctrl:1
	v_fma_f32 v137, -v145, v190, v137
	v_fma_f32 v138, -v145, v191, v138
	v_fma_f32 v139, -v145, v192, v139
	v_fma_f32 v140, -v145, v193, v140
	v_fma_f32 v2, v2, v194, v137
	v_fma_f32 v13, v13, v195, v138
	v_fma_f32 v12, v12, v196, v139
	v_fma_f32 v8, v8, v197, v140
	s_waitcnt lgkmcnt(6)
	v_mul_f32 v137, v228, v220
	v_mul_f32 v138, v228, v221
	v_mul_f32 v145, v2, v208
	v_fma_f32 v145, v13, v209, v145
	v_fma_f32 v145, v12, v210, v145
	v_fma_f32 v145, v8, v211, v145
	ds_read_b128 v[164:167], v10 offset:30720
	ds_read_b128 v[168:171], v10 offset:30976
	ds_read_b128 v[172:175], v10 offset:31232
	ds_read_b128 v[176:179], v10 offset:31488
	ds_read_b128 v[180:183], v10 offset:31744
	ds_read_b32 v184, v11 offset:30720
	v_add_f32_dpp v145, v145, v145 quad_perm:[1,0,3,2] row_mask:0xf bank_mask:0xf bound_ctrl:1
	v_mul_f32 v149, v2, v202
	v_fma_f32 v149, v13, v203, v149
	v_add_f32_dpp v145, v145, v145 quad_perm:[2,3,0,1] row_mask:0xf bank_mask:0xf bound_ctrl:1
	v_fma_f32 v149, v12, v204, v149
	v_fma_f32 v149, v8, v205, v149
	v_add_f32_dpp v145, v145, v145 row_half_mirror row_mask:0xf bank_mask:0xf bound_ctrl:1
	v_mul_f32 v139, v228, v222
	v_mul_f32 v140, v228, v223
	v_add_f32_dpp v145, v145, v145 row_mirror row_mask:0xf bank_mask:0xf bound_ctrl:1
	v_fma_f32 v137, -v145, v212, v137
	v_fma_f32 v138, -v145, v213, v138
	v_fma_f32 v139, -v145, v214, v139
	v_fma_f32 v140, -v145, v215, v140
	v_fma_f32 v2, v2, v216, v137
	v_fma_f32 v13, v13, v217, v138
	v_fma_f32 v12, v12, v218, v139
	v_fma_f32 v8, v8, v219, v140
	s_waitcnt lgkmcnt(6)
	v_mul_f32 v137, v250, v242
	v_mul_f32 v138, v250, v243
	v_mul_f32 v145, v2, v230
	v_fma_f32 v145, v13, v231, v145
	v_fma_f32 v145, v12, v232, v145
	v_fma_f32 v145, v8, v233, v145
	ds_read_b128 v[186:189], v10 offset:32256
	ds_read_b128 v[190:193], v10 offset:32512
	ds_read_b128 v[194:197], v10 offset:32768
	ds_read_b128 v[198:201], v10 offset:33024
	ds_read_b128 v[202:205], v10 offset:33280
	ds_read_b32 v206, v11 offset:32256
	v_add_f32_dpp v145, v145, v145 quad_perm:[1,0,3,2] row_mask:0xf bank_mask:0xf bound_ctrl:1
	v_mul_f32 v150, v2, v224
	v_fma_f32 v150, v13, v225, v150
	v_add_f32_dpp v145, v145, v145 quad_perm:[2,3,0,1] row_mask:0xf bank_mask:0xf bound_ctrl:1
	v_fma_f32 v150, v12, v226, v150
	v_fma_f32 v150, v8, v227, v150
	v_add_f32_dpp v145, v145, v145 row_half_mirror row_mask:0xf bank_mask:0xf bound_ctrl:1
	v_mul_f32 v139, v250, v244
	v_mul_f32 v140, v250, v245
	v_add_f32_dpp v145, v145, v145 row_mirror row_mask:0xf bank_mask:0xf bound_ctrl:1
	v_fma_f32 v137, -v145, v234, v137
	v_fma_f32 v138, -v145, v235, v138
	v_fma_f32 v139, -v145, v236, v139
	v_fma_f32 v140, -v145, v237, v140
	v_fma_f32 v2, v2, v238, v137
	v_fma_f32 v13, v13, v239, v138
	v_fma_f32 v12, v12, v240, v139
	v_fma_f32 v8, v8, v241, v140
	s_waitcnt lgkmcnt(6)
	v_mul_f32 v137, v184, v176
	v_mul_f32 v138, v184, v177
	v_mul_f32 v145, v2, v164
	v_fma_f32 v145, v13, v165, v145
	v_fma_f32 v145, v12, v166, v145
	v_fma_f32 v145, v8, v167, v145
	ds_read_b128 v[208:211], v10 offset:33792
	ds_read_b128 v[212:215], v10 offset:34048
	ds_read_b128 v[216:219], v10 offset:34304
	ds_read_b128 v[220:223], v10 offset:34560
	ds_read_b128 v[224:227], v10 offset:34816
	ds_read_b32 v228, v11 offset:33792
	v_add_f32_dpp v145, v145, v145 quad_perm:[1,0,3,2] row_mask:0xf bank_mask:0xf bound_ctrl:1
	v_mul_f32 v151, v2, v246
	v_fma_f32 v151, v13, v247, v151
	v_add_f32_dpp v145, v145, v145 quad_perm:[2,3,0,1] row_mask:0xf bank_mask:0xf bound_ctrl:1
	v_fma_f32 v151, v12, v248, v151
	v_fma_f32 v151, v8, v249, v151
	v_add_f32_dpp v145, v145, v145 row_half_mirror row_mask:0xf bank_mask:0xf bound_ctrl:1
	v_mul_f32 v139, v184, v178
	v_mul_f32 v140, v184, v179
	v_add_f32_dpp v145, v145, v145 row_mirror row_mask:0xf bank_mask:0xf bound_ctrl:1
	v_fma_f32 v137, -v145, v168, v137
	v_fma_f32 v138, -v145, v169, v138
	v_fma_f32 v139, -v145, v170, v139
	v_fma_f32 v140, -v145, v171, v140
	v_fma_f32 v2, v2, v172, v137
	v_fma_f32 v13, v13, v173, v138
	v_fma_f32 v12, v12, v174, v139
	v_fma_f32 v8, v8, v175, v140
	s_waitcnt lgkmcnt(6)
	v_mul_f32 v137, v206, v198
	v_mul_f32 v138, v206, v199
	v_mul_f32 v145, v2, v186
	v_fma_f32 v145, v13, v187, v145
	v_fma_f32 v145, v12, v188, v145
	v_fma_f32 v145, v8, v189, v145
	ds_read_b128 v[230:233], v10 offset:35328
	ds_read_b128 v[234:237], v10 offset:35584
	ds_read_b128 v[238:241], v10 offset:35840
	ds_read_b128 v[242:245], v10 offset:36096
	ds_read_b128 v[246:249], v10 offset:36352
	ds_read_b32 v250, v11 offset:35328
	v_add_f32_dpp v145, v145, v145 quad_perm:[1,0,3,2] row_mask:0xf bank_mask:0xf bound_ctrl:1
	v_mul_f32 v152, v2, v180
	v_fma_f32 v152, v13, v181, v152
	v_add_f32_dpp v145, v145, v145 quad_perm:[2,3,0,1] row_mask:0xf bank_mask:0xf bound_ctrl:1
	v_fma_f32 v152, v12, v182, v152
	v_fma_f32 v152, v8, v183, v152
	v_add_f32_dpp v145, v145, v145 row_half_mirror row_mask:0xf bank_mask:0xf bound_ctrl:1
	v_mul_f32 v139, v206, v200
	v_mul_f32 v140, v206, v201
	v_add_f32_dpp v145, v145, v145 row_mirror row_mask:0xf bank_mask:0xf bound_ctrl:1
	v_fma_f32 v137, -v145, v190, v137
	v_fma_f32 v138, -v145, v191, v138
	v_fma_f32 v139, -v145, v192, v139
	v_fma_f32 v140, -v145, v193, v140
	v_fma_f32 v2, v2, v194, v137
	v_fma_f32 v13, v13, v195, v138
	v_fma_f32 v12, v12, v196, v139
	v_fma_f32 v8, v8, v197, v140
	s_waitcnt lgkmcnt(6)
	v_mul_f32 v137, v228, v220
	v_mul_f32 v138, v228, v221
	v_mul_f32 v145, v2, v208
	v_fma_f32 v145, v13, v209, v145
	v_fma_f32 v145, v12, v210, v145
	v_fma_f32 v145, v8, v211, v145
	ds_read_b128 v[164:167], v10 offset:36864
	ds_read_b128 v[168:171], v10 offset:37120
	ds_read_b128 v[172:175], v10 offset:37376
	ds_read_b128 v[176:179], v10 offset:37632
	ds_read_b128 v[180:183], v10 offset:37888
	ds_read_b32 v184, v11 offset:36864
	v_add_f32_dpp v145, v145, v145 quad_perm:[1,0,3,2] row_mask:0xf bank_mask:0xf bound_ctrl:1
	v_mul_f32 v153, v2, v202
	v_fma_f32 v153, v13, v203, v153
	v_add_f32_dpp v145, v145, v145 quad_perm:[2,3,0,1] row_mask:0xf bank_mask:0xf bound_ctrl:1
	v_fma_f32 v153, v12, v204, v153
	v_fma_f32 v153, v8, v205, v153
	v_add_f32_dpp v145, v145, v145 row_half_mirror row_mask:0xf bank_mask:0xf bound_ctrl:1
	v_mul_f32 v139, v228, v222
	v_mul_f32 v140, v228, v223
	v_add_f32_dpp v145, v145, v145 row_mirror row_mask:0xf bank_mask:0xf bound_ctrl:1
	v_fma_f32 v137, -v145, v212, v137
	v_fma_f32 v138, -v145, v213, v138
	v_fma_f32 v139, -v145, v214, v139
	v_fma_f32 v140, -v145, v215, v140
	v_fma_f32 v2, v2, v216, v137
	v_fma_f32 v13, v13, v217, v138
	v_fma_f32 v12, v12, v218, v139
	v_fma_f32 v8, v8, v219, v140
	s_waitcnt lgkmcnt(6)
	v_mul_f32 v137, v250, v242
	v_mul_f32 v138, v250, v243
	v_mul_f32 v145, v2, v230
	v_fma_f32 v145, v13, v231, v145
	v_fma_f32 v145, v12, v232, v145
	v_fma_f32 v145, v8, v233, v145
	ds_read_b128 v[186:189], v10 offset:38400
	ds_read_b128 v[190:193], v10 offset:38656
	ds_read_b128 v[194:197], v10 offset:38912
	ds_read_b128 v[198:201], v10 offset:39168
	ds_read_b128 v[202:205], v10 offset:39424
	ds_read_b32 v206, v11 offset:38400
	v_add_f32_dpp v145, v145, v145 quad_perm:[1,0,3,2] row_mask:0xf bank_mask:0xf bound_ctrl:1
	v_mul_f32 v154, v2, v224
	v_fma_f32 v154, v13, v225, v154
	v_add_f32_dpp v145, v145, v145 quad_perm:[2,3,0,1] row_mask:0xf bank_mask:0xf bound_ctrl:1
	v_fma_f32 v154, v12, v226, v154
	v_fma_f32 v154, v8, v227, v154
	v_add_f32_dpp v145, v145, v145 row_half_mirror row_mask:0xf bank_mask:0xf bound_ctrl:1
	v_mul_f32 v139, v250, v244
	v_mul_f32 v140, v250, v245
	v_add_f32_dpp v145, v145, v145 row_mirror row_mask:0xf bank_mask:0xf bound_ctrl:1
	v_fma_f32 v137, -v145, v234, v137
	v_fma_f32 v138, -v145, v235, v138
	v_fma_f32 v139, -v145, v236, v139
	v_fma_f32 v140, -v145, v237, v140
	v_fma_f32 v2, v2, v238, v137
	v_fma_f32 v13, v13, v239, v138
	v_fma_f32 v12, v12, v240, v139
	v_fma_f32 v8, v8, v241, v140
	s_waitcnt lgkmcnt(6)
	v_mul_f32 v137, v184, v176
	v_mul_f32 v138, v184, v177
	v_mul_f32 v145, v2, v164
	v_fma_f32 v145, v13, v165, v145
	v_fma_f32 v145, v12, v166, v145
	v_fma_f32 v145, v8, v167, v145
	ds_read_b128 v[208:211], v10 offset:39936
	ds_read_b128 v[212:215], v10 offset:40192
	ds_read_b128 v[216:219], v10 offset:40448
	ds_read_b128 v[220:223], v10 offset:40704
	ds_read_b128 v[224:227], v10 offset:40960
	ds_read_b32 v228, v11 offset:39936
	v_add_f32_dpp v145, v145, v145 quad_perm:[1,0,3,2] row_mask:0xf bank_mask:0xf bound_ctrl:1
	v_mul_f32 v155, v2, v246
	v_fma_f32 v155, v13, v247, v155
	v_add_f32_dpp v145, v145, v145 quad_perm:[2,3,0,1] row_mask:0xf bank_mask:0xf bound_ctrl:1
	v_fma_f32 v155, v12, v248, v155
	v_fma_f32 v155, v8, v249, v155
	v_add_f32_dpp v145, v145, v145 row_half_mirror row_mask:0xf bank_mask:0xf bound_ctrl:1
	v_mul_f32 v139, v184, v178
	v_mul_f32 v140, v184, v179
	v_add_f32_dpp v145, v145, v145 row_mirror row_mask:0xf bank_mask:0xf bound_ctrl:1
	v_fma_f32 v137, -v145, v168, v137
	v_fma_f32 v138, -v145, v169, v138
	v_fma_f32 v139, -v145, v170, v139
	v_fma_f32 v140, -v145, v171, v140
	v_fma_f32 v2, v2, v172, v137
	v_fma_f32 v13, v13, v173, v138
	v_fma_f32 v12, v12, v174, v139
	v_fma_f32 v8, v8, v175, v140
	s_waitcnt lgkmcnt(6)
	v_mul_f32 v137, v206, v198
	v_mul_f32 v138, v206, v199
	v_mul_f32 v145, v2, v186
	v_fma_f32 v145, v13, v187, v145
	v_fma_f32 v145, v12, v188, v145
	v_fma_f32 v145, v8, v189, v145
	ds_read_b128 v[230:233], v10 offset:41472
	ds_read_b128 v[234:237], v10 offset:41728
	ds_read_b128 v[238:241], v10 offset:41984
	ds_read_b128 v[242:245], v10 offset:42240
	ds_read_b128 v[246:249], v10 offset:42496
	ds_read_b32 v250, v11 offset:41472
	v_add_f32_dpp v145, v145, v145 quad_perm:[1,0,3,2] row_mask:0xf bank_mask:0xf bound_ctrl:1
	v_mul_f32 v156, v2, v180
	v_fma_f32 v156, v13, v181, v156
	v_add_f32_dpp v145, v145, v145 quad_perm:[2,3,0,1] row_mask:0xf bank_mask:0xf bound_ctrl:1
	v_fma_f32 v156, v12, v182, v156
	v_fma_f32 v156, v8, v183, v156
	v_add_f32_dpp v145, v145, v145 row_half_mirror row_mask:0xf bank_mask:0xf bound_ctrl:1
	v_mul_f32 v139, v206, v200
	v_mul_f32 v140, v206, v201
	v_add_f32_dpp v145, v145, v145 row_mirror row_mask:0xf bank_mask:0xf bound_ctrl:1
	v_fma_f32 v137, -v145, v190, v137
	v_fma_f32 v138, -v145, v191, v138
	v_fma_f32 v139, -v145, v192, v139
	v_fma_f32 v140, -v145, v193, v140
	v_fma_f32 v2, v2, v194, v137
	v_fma_f32 v13, v13, v195, v138
	v_fma_f32 v12, v12, v196, v139
	v_fma_f32 v8, v8, v197, v140
	s_waitcnt lgkmcnt(6)
	v_mul_f32 v137, v228, v220
	v_mul_f32 v138, v228, v221
	v_mul_f32 v145, v2, v208
	v_fma_f32 v145, v13, v209, v145
	v_fma_f32 v145, v12, v210, v145
	v_fma_f32 v145, v8, v211, v145
	ds_read_b128 v[164:167], v10 offset:43008
	ds_read_b128 v[168:171], v10 offset:43264
	ds_read_b128 v[172:175], v10 offset:43520
	ds_read_b128 v[176:179], v10 offset:43776
	ds_read_b128 v[180:183], v10 offset:44032
	ds_read_b32 v184, v11 offset:43008
	v_add_f32_dpp v145, v145, v145 quad_perm:[1,0,3,2] row_mask:0xf bank_mask:0xf bound_ctrl:1
	v_mul_f32 v157, v2, v202
	v_fma_f32 v157, v13, v203, v157
	v_add_f32_dpp v145, v145, v145 quad_perm:[2,3,0,1] row_mask:0xf bank_mask:0xf bound_ctrl:1
	v_fma_f32 v157, v12, v204, v157
	v_fma_f32 v157, v8, v205, v157
	v_add_f32_dpp v145, v145, v145 row_half_mirror row_mask:0xf bank_mask:0xf bound_ctrl:1
	v_mul_f32 v139, v228, v222
	v_mul_f32 v140, v228, v223
	v_add_f32_dpp v145, v145, v145 row_mirror row_mask:0xf bank_mask:0xf bound_ctrl:1
	v_fma_f32 v137, -v145, v212, v137
	v_fma_f32 v138, -v145, v213, v138
	v_fma_f32 v139, -v145, v214, v139
	v_fma_f32 v140, -v145, v215, v140
	v_fma_f32 v2, v2, v216, v137
	v_fma_f32 v13, v13, v217, v138
	v_fma_f32 v12, v12, v218, v139
	v_fma_f32 v8, v8, v219, v140
	s_waitcnt lgkmcnt(6)
	v_mul_f32 v137, v250, v242
	v_mul_f32 v138, v250, v243
	v_mul_f32 v145, v2, v230
	v_fma_f32 v145, v13, v231, v145
	v_fma_f32 v145, v12, v232, v145
	v_fma_f32 v145, v8, v233, v145
	ds_read_b128 v[186:189], v10 offset:44544
	ds_read_b128 v[190:193], v10 offset:44800
	ds_read_b128 v[194:197], v10 offset:45056
	ds_read_b128 v[198:201], v10 offset:45312
	ds_read_b128 v[202:205], v10 offset:45568
	ds_read_b32 v206, v11 offset:44544
	v_add_f32_dpp v145, v145, v145 quad_perm:[1,0,3,2] row_mask:0xf bank_mask:0xf bound_ctrl:1
	v_mul_f32 v158, v2, v224
	v_fma_f32 v158, v13, v225, v158
	v_add_f32_dpp v145, v145, v145 quad_perm:[2,3,0,1] row_mask:0xf bank_mask:0xf bound_ctrl:1
	v_fma_f32 v158, v12, v226, v158
	v_fma_f32 v158, v8, v227, v158
	v_add_f32_dpp v145, v145, v145 row_half_mirror row_mask:0xf bank_mask:0xf bound_ctrl:1
	v_mul_f32 v139, v250, v244
	v_mul_f32 v140, v250, v245
	v_add_f32_dpp v145, v145, v145 row_mirror row_mask:0xf bank_mask:0xf bound_ctrl:1
	v_fma_f32 v137, -v145, v234, v137
	v_fma_f32 v138, -v145, v235, v138
	v_fma_f32 v139, -v145, v236, v139
	v_fma_f32 v140, -v145, v237, v140
	v_fma_f32 v2, v2, v238, v137
	v_fma_f32 v13, v13, v239, v138
	v_fma_f32 v12, v12, v240, v139
	v_fma_f32 v8, v8, v241, v140
	s_waitcnt lgkmcnt(6)
	v_mul_f32 v137, v184, v176
	v_mul_f32 v138, v184, v177
	v_mul_f32 v145, v2, v164
	v_fma_f32 v145, v13, v165, v145
	v_fma_f32 v145, v12, v166, v145
	v_fma_f32 v145, v8, v167, v145
	ds_read_b128 v[208:211], v10 offset:46080
	ds_read_b128 v[212:215], v10 offset:46336
	ds_read_b128 v[216:219], v10 offset:46592
	ds_read_b128 v[220:223], v10 offset:46848
	ds_read_b128 v[224:227], v10 offset:47104
	ds_read_b32 v228, v11 offset:46080
	v_add_f32_dpp v145, v145, v145 quad_perm:[1,0,3,2] row_mask:0xf bank_mask:0xf bound_ctrl:1
	v_mul_f32 v159, v2, v246
	v_fma_f32 v159, v13, v247, v159
	v_add_f32_dpp v145, v145, v145 quad_perm:[2,3,0,1] row_mask:0xf bank_mask:0xf bound_ctrl:1
	v_fma_f32 v159, v12, v248, v159
	v_fma_f32 v159, v8, v249, v159
	v_add_f32_dpp v145, v145, v145 row_half_mirror row_mask:0xf bank_mask:0xf bound_ctrl:1
	v_mul_f32 v139, v184, v178
	v_mul_f32 v140, v184, v179
	v_add_f32_dpp v145, v145, v145 row_mirror row_mask:0xf bank_mask:0xf bound_ctrl:1
	v_fma_f32 v137, -v145, v168, v137
	v_fma_f32 v138, -v145, v169, v138
	v_fma_f32 v139, -v145, v170, v139
	v_fma_f32 v140, -v145, v171, v140
	v_fma_f32 v2, v2, v172, v137
	v_fma_f32 v13, v13, v173, v138
	v_fma_f32 v12, v12, v174, v139
	v_fma_f32 v8, v8, v175, v140
	s_waitcnt lgkmcnt(6)
	v_mul_f32 v137, v206, v198
	v_mul_f32 v138, v206, v199
	v_mul_f32 v145, v2, v186
	v_fma_f32 v145, v13, v187, v145
	v_fma_f32 v145, v12, v188, v145
	v_fma_f32 v145, v8, v189, v145
	ds_read_b128 v[230:233], v10 offset:47616
	ds_read_b128 v[234:237], v10 offset:47872
	ds_read_b128 v[238:241], v10 offset:48128
	ds_read_b128 v[242:245], v10 offset:48384
	ds_read_b128 v[246:249], v10 offset:48640
	ds_read_b32 v250, v11 offset:47616
	v_add_f32_dpp v145, v145, v145 quad_perm:[1,0,3,2] row_mask:0xf bank_mask:0xf bound_ctrl:1
	v_mul_f32 v160, v2, v180
	v_fma_f32 v160, v13, v181, v160
	v_add_f32_dpp v145, v145, v145 quad_perm:[2,3,0,1] row_mask:0xf bank_mask:0xf bound_ctrl:1
	v_fma_f32 v160, v12, v182, v160
	v_fma_f32 v160, v8, v183, v160
	v_add_f32_dpp v145, v145, v145 row_half_mirror row_mask:0xf bank_mask:0xf bound_ctrl:1
	v_mul_f32 v139, v206, v200
	v_mul_f32 v140, v206, v201
	v_add_f32_dpp v145, v145, v145 row_mirror row_mask:0xf bank_mask:0xf bound_ctrl:1
	v_fma_f32 v137, -v145, v190, v137
	v_fma_f32 v138, -v145, v191, v138
	v_fma_f32 v139, -v145, v192, v139
	v_fma_f32 v140, -v145, v193, v140
	v_fma_f32 v2, v2, v194, v137
	v_fma_f32 v13, v13, v195, v138
	v_fma_f32 v12, v12, v196, v139
	v_fma_f32 v8, v8, v197, v140
	s_waitcnt lgkmcnt(6)
	v_mul_f32 v137, v228, v220
	v_mul_f32 v138, v228, v221
	v_mul_f32 v145, v2, v208
	v_fma_f32 v145, v13, v209, v145
	v_fma_f32 v145, v12, v210, v145
	v_fma_f32 v145, v8, v211, v145
	s_nop 1
	v_add_f32_dpp v145, v145, v145 quad_perm:[1,0,3,2] row_mask:0xf bank_mask:0xf bound_ctrl:1
	v_mul_f32 v161, v2, v202
	v_fma_f32 v161, v13, v203, v161
	v_add_f32_dpp v145, v145, v145 quad_perm:[2,3,0,1] row_mask:0xf bank_mask:0xf bound_ctrl:1
	v_fma_f32 v161, v12, v204, v161
	v_fma_f32 v161, v8, v205, v161
	v_add_f32_dpp v145, v145, v145 row_half_mirror row_mask:0xf bank_mask:0xf bound_ctrl:1
	v_mul_f32 v139, v228, v222
	v_mul_f32 v140, v228, v223
	v_add_f32_dpp v145, v145, v145 row_mirror row_mask:0xf bank_mask:0xf bound_ctrl:1
	v_fma_f32 v137, -v145, v212, v137
	v_fma_f32 v138, -v145, v213, v138
	v_fma_f32 v139, -v145, v214, v139
	v_fma_f32 v140, -v145, v215, v140
	v_fma_f32 v2, v2, v216, v137
	v_fma_f32 v13, v13, v217, v138
	v_fma_f32 v12, v12, v218, v139
	v_fma_f32 v8, v8, v219, v140
	s_waitcnt lgkmcnt(0)
	v_mul_f32 v137, v250, v242
	v_mul_f32 v138, v250, v243
	v_mul_f32 v145, v2, v230
	v_fma_f32 v145, v13, v231, v145
	v_fma_f32 v145, v12, v232, v145
	v_fma_f32 v145, v8, v233, v145
	s_nop 1
	v_add_f32_dpp v145, v145, v145 quad_perm:[1,0,3,2] row_mask:0xf bank_mask:0xf bound_ctrl:1
	v_mul_f32 v162, v2, v224
	v_fma_f32 v162, v13, v225, v162
	v_add_f32_dpp v145, v145, v145 quad_perm:[2,3,0,1] row_mask:0xf bank_mask:0xf bound_ctrl:1
	v_fma_f32 v162, v12, v226, v162
	v_fma_f32 v162, v8, v227, v162
	v_add_f32_dpp v145, v145, v145 row_half_mirror row_mask:0xf bank_mask:0xf bound_ctrl:1
	v_mul_f32 v139, v250, v244
	v_mul_f32 v140, v250, v245
	v_add_f32_dpp v145, v145, v145 row_mirror row_mask:0xf bank_mask:0xf bound_ctrl:1
	v_fma_f32 v137, -v145, v234, v137
	v_fma_f32 v138, -v145, v235, v138
	v_fma_f32 v139, -v145, v236, v139
	v_fma_f32 v140, -v145, v237, v140
	v_fma_f32 v2, v2, v238, v137
	v_fma_f32 v13, v13, v239, v138
	v_fma_f32 v12, v12, v240, v139
	v_fma_f32 v8, v8, v241, v140
	v_mul_f32 v163, v2, v246
	v_fma_f32 v163, v13, v247, v163
	v_fma_f32 v163, v12, v248, v163
	v_fma_f32 v163, v8, v249, v163
	s_nop 0
	v_and_b32 v244, 8, v3
	v_cmp_ne_u32 vcc, 0, v244
	v_cndmask_b32 v244, v156, v148, vcc
	v_cndmask_b32 v245, v157, v149, vcc
	v_cndmask_b32 v246, v158, v150, vcc
	v_cndmask_b32 v247, v159, v151, vcc
	v_cndmask_b32 v230, v148, v156, vcc
	v_cndmask_b32 v231, v149, v157, vcc
	v_cndmask_b32 v232, v150, v158, vcc
	v_cndmask_b32 v233, v151, v159, vcc
	v_add_f32_dpp v230, v244, v230 row_mirror row_mask:0xf bank_mask:0xf bound_ctrl:1
	v_add_f32_dpp v231, v245, v231 row_mirror row_mask:0xf bank_mask:0xf bound_ctrl:1
	v_add_f32_dpp v232, v246, v232 row_mirror row_mask:0xf bank_mask:0xf bound_ctrl:1
	v_add_f32_dpp v233, v247, v233 row_mirror row_mask:0xf bank_mask:0xf bound_ctrl:1
	v_cndmask_b32 v244, v160, v152, vcc
	v_cndmask_b32 v245, v161, v153, vcc
	v_cndmask_b32 v246, v162, v154, vcc
	v_cndmask_b32 v247, v163, v155, vcc
	v_cndmask_b32 v234, v152, v160, vcc
	v_cndmask_b32 v235, v153, v161, vcc
	v_cndmask_b32 v236, v154, v162, vcc
	v_cndmask_b32 v237, v155, v163, vcc
	v_add_f32_dpp v234, v244, v234 row_mirror row_mask:0xf bank_mask:0xf bound_ctrl:1
	v_add_f32_dpp v235, v245, v235 row_mirror row_mask:0xf bank_mask:0xf bound_ctrl:1
	v_add_f32_dpp v236, v246, v236 row_mirror row_mask:0xf bank_mask:0xf bound_ctrl:1
	v_add_f32_dpp v237, v247, v237 row_mirror row_mask:0xf bank_mask:0xf bound_ctrl:1
	v_and_b32 v244, 4, v3
	v_cmp_ne_u32 vcc, 0, v244
	v_cndmask_b32 v244, v234, v230, vcc
	v_cndmask_b32 v245, v235, v231, vcc
	v_cndmask_b32 v246, v236, v232, vcc
	v_cndmask_b32 v247, v237, v233, vcc
	v_cndmask_b32 v238, v230, v234, vcc
	v_cndmask_b32 v239, v231, v235, vcc
	v_cndmask_b32 v240, v232, v236, vcc
	v_cndmask_b32 v241, v233, v237, vcc
	v_add_f32_dpp v238, v244, v238 row_half_mirror row_mask:0xf bank_mask:0xf bound_ctrl:1
	v_add_f32_dpp v239, v245, v239 row_half_mirror row_mask:0xf bank_mask:0xf bound_ctrl:1
	v_add_f32_dpp v240, v246, v240 row_half_mirror row_mask:0xf bank_mask:0xf bound_ctrl:1
	v_add_f32_dpp v241, v247, v241 row_half_mirror row_mask:0xf bank_mask:0xf bound_ctrl:1
	v_and_b32 v244, 2, v3
	v_cmp_ne_u32 vcc, 0, v244
	v_cndmask_b32 v244, v240, v238, vcc
	v_cndmask_b32 v245, v241, v239, vcc
	v_cndmask_b32 v242, v238, v240, vcc
	v_cndmask_b32 v243, v239, v241, vcc
	v_add_f32_dpp v242, v244, v242 quad_perm:[2,3,0,1] row_mask:0xf bank_mask:0xf bound_ctrl:1
	v_add_f32_dpp v243, v245, v243 quad_perm:[2,3,0,1] row_mask:0xf bank_mask:0xf bound_ctrl:1
	v_and_b32 v244, 1, v3
	v_cmp_ne_u32 vcc, 0, v244
	v_cndmask_b32 v244, v243, v242, vcc
	v_cndmask_b32 v245, v242, v243, vcc
	s_nop 0
	v_add_f32_dpp v19, v244, v245 quad_perm:[1,0,3,2] row_mask:0xf bank_mask:0xf bound_ctrl:1

; #define SCAN_BAR() asm volatile("s_barrier" ::: "memory")
; __device__ __forceinline__ void scan_unit(const Ctx& C0, const float* scn, int T, int quarter, const float* S0, float* Sout, unsigned char* obase, int mode) {
;     ...
;         for (int k = 0; k < nch; ++k) {
;             const unsigned aq = (unsigned)(size_t)(C.lds + (k & 1) * SLOT_B) + 16u * (unsigned)q, av = (unsigned)(size_t)(C.lds + (k & 1) * SLOT_B) + (320u + (unsigned)irow) * 4u;
;             float osel0, osel1;
;             asm volatile(SCAN_CHUNK_ASM : "+v"(S0x), "+v"(S1x), "+v"(S2x), "+v"(S3x), "=&v"(osel0), "=&v"(osel1) : "v"(aq), "v"(av), "v"(q) : SCAN_CHUNK_CLOBBERS, "memory");
;             if (mode == 0) { *(float*)(obase + (size_t)(k * 32 + q) * UPITCH_B + rl * 4) = osel0; *(float*)(obase + (size_t)(k * 32 + 16 + q) * UPITCH_B + rl * 4) = osel1; }
;             SCAN_BAR();
;         }
;         if (mode == 0) *(f32x4*)(Sout + irow * 64 + 4 * q) = (f32x4){S0x, S1x, S2x, S3x};
	s_addc_u32 s1, s1, 0
	v_add_co_u32_e32 v16, vcc, s8, v14
	s_cmp_lg_u32 s0, 0x5600000
	s_nop 0
	v_addc_co_u32_e32 v17, vcc, 0, v15, vcc
	v_add_co_u32_e32 v14, vcc, 0xfcaa000, v14
	global_store_dword v[16:17], v18, off offset:768
	s_nop 0
	v_addc_co_u32_e32 v15, vcc, 0, v15, vcc
	global_store_dword v[14:15], v19, off offset:768
	s_barrier
	s_cbranch_scc1 .LBB0_685
	v_readlane_b32 s0, v255, 46
	s_add_i32 s0, s3, s0
	s_ashr_i32 s1, s0, 31
	s_lshl_b64 s[0:1], s[0:1], 17
	v_readlane_b32 s3, v253, 26
	s_add_u32 s0, s3, s0
	v_readlane_b32 s3, v253, 27
	s_addc_u32 s1, s3, s1
	s_lshl_b32 s2, s2, 14
	s_add_u32 s0, s0, s2
	s_addc_u32 s1, s1, 0
	v_lshlrev_b32_e32 v0, 8, v0
	v_lshl_add_u64 v[6:7], s[0:1], 0, v[0:1]
	v_mov_b32_e32 v5, v1
	v_lshl_add_u64 v[6:7], v[6:7], 0, v[4:5]
	v_mov_b32_e32 v3, v13
	v_mov_b32_e32 v4, v12
	v_mov_b32_e32 v5, v8
	global_store_dwordx4 v[6:7], v[2:5], off
